# MLA loop role-split (waves 0-3 matrix-then-softmax, waves 4-7 softmax-then-matrix), default priorities
# speedup vs baseline: 1.0052x; 1.0052x over previous
; __device__ __forceinline__ float xhalf_max(float m) { auto rr = __builtin_amdgcn_permlane32_swap(__float_as_uint(m), __float_as_uint(m), false, false); return fmaxf(__uint_as_float(rr[0]), __uint_as_float(rr[1])); }
; template <int GRP, bool has_next> __device__ __forceinline__ void att_step(const AttCtx<GRP>& C, AttState<GRP>& S, int s, f32x16& P0, f32x16& P1, f32x16& PN0, f32x16& PN1, u32x4& kreg, u32x4& preg, u32x4& vreg) {
;     ...
;     if ((t & 7) == 0) {
;         float ma = max3f(P0[0], P0[1], P0[2]), mb = max3f(P0[3], P0[4], P0[5]), mc = max3f(P1[0], P1[1], P1[2]), md = max3f(P1[3], P1[4], P1[5]);
;         ma = max3f(ma, P0[6], P0[7]); mb = max3f(mb, P0[8], P0[9]); mc = max3f(mc, P1[6], P1[7]); md = max3f(md, P1[8], P1[9]);
;         ma = max3f(ma, P0[10], P0[11]); mb = max3f(mb, P0[12], P0[13]); mc = max3f(mc, P1[10], P1[11]); md = max3f(md, P1[12], P1[13]);
;         ma = max3f(ma, P0[14], P0[15]); mc = max3f(mc, P1[14], P1[15]); ma = max3f(ma, mb, mc); mb = md;
;         const float mx = xhalf_max(max2f(ma, mb));
;         const int up = __any(mx > THR), dn = (t == 0) ? __any(mx < -THR) : 0;
; template <int GRP> ...
;     ...
;     S.o0 = (f32x16){}; S.o1 = (f32x16){}; S.mhat = 0.f; S.lrun = 0.f; S.ssq = 0.f; S.refnz = 0;
; #pragma unroll
;     for (int i = 0; i < 16; ++i) S.pw[i] = 0u;
;     { u32x4 kB, pB = {0u, 0u, 0u, 0u};
;       att_ldk<GRP>(C, 0, kA, pA); att_ldk<GRP>(C, 1, kB, pB); att_ldv<GRP>(C, 0, vA);
;       att_stk<GRP>(C, 0, kA, pA); att_stk<GRP>(C, 1, kB, pB); att_stv<GRP>(C, 0, vA); }
;     att_ldk<GRP>(C, 2, kA, pA); att_ldv<GRP>(C, 1, vA);
; #pragma unroll
;     for (int ks = 0; ks < NKS; ++ks) S.qr[ks] = *(const bf16x8*)(Q + C.qrow * QP + C.h0 * DK + ks * 16 + hi * 8);
;     ATT_BAR();
;     f32x16 pa0 = {}, pa1 = {}, pb0 = {}, pb1 = {};
;     {
;         bf16x8 kf[2 * NKS]; att_kfrag<GRP, 0, NKS>(C, 0, kf);
; #pragma unroll
;         for (int ks = 0; ks < NKS; ++ks) { pa0 = __builtin_amdgcn_mfma_f32_32x32x16_bf16(kf[2 * ks], S.qr[ks], pa0, 0, 0, 0); pa1 = __builtin_amdgcn_mfma_f32_32x32x16_bf16(kf[2 * ks + 1], S.qr[ks], pa1, 0, 0, 0); }
;     }
;     if (wid >= 4) __builtin_amdgcn_s_setprio(1);
;     asm volatile("s_nop 15\n\ts_nop 7" : "+v"(pa0), "+v"(pa1));
;     for (int s = 0; s < NSTEP - 2; s += 2) { att_step<GRP, true>(C, S, s, pa0, pa1, pb0, pb1, kA, pA, vA); att_step<GRP, true>(C, S, s + 1, pb0, pb1, pa0, pa1, kA, pA, vA); }
.LBB0_775:
	v_lshlrev_b32_e32 v4, 3, v2
	s_and_b32 s0, s58, 7
	v_mad_u32_u24 v3, v3, s37, v96
	v_mad_u64_u32 v[6:7], s[14:15], v16, s37, v[18:19]
	v_lshlrev_b32_e32 v96, 1, v4
	s_lshl_b32 s62, s0, 22
	s_lshl_b32 s60, s66, 2
	v_lshl_add_u64 v[164:165], v[0:1], 0, v[96:97]
	v_lshlrev_b64 v[0:1], 7, v[16:17]
	s_lshl_b64 s[14:15], s[10:11], 1
	v_lshlrev_b64 v[8:9], 11, v[152:153]
	v_lshl_add_u64 v[0:1], s[62:63], 0, v[0:1]
	s_add_u32 s14, s8, s14
	v_mov_b32_e32 v5, v97
	v_lshl_add_u64 v[154:155], s[48:49], 0, v[8:9]
	v_lshl_or_b32 v0, v19, 4, v0
	s_addc_u32 s15, s9, s15
	v_mov_b32_e32 v175, 0
	s_mov_b32 s72, 0
	v_cmp_eq_u32_e64 s[0:1], 0, v2
	v_lshlrev_b32_e32 v156, 2, v2
	v_lshl_add_u64 v[162:163], v[154:155], 0, v[4:5]
	v_lshl_add_u64 v[166:167], s[14:15], 0, v[0:1]
	s_add_i32 s70, s10, 0x4000
	s_movk_i32 s67, 0x2000
	v_add_u32_e32 v157, 0, v3
	v_add_u32_e32 v169, 0, v6
	v_mov_b32_e32 v168, 0
	s_mov_b32 s69, 0
	v_mov_b32_e32 v170, 0
	v_mov_b32_e32 v0, 0
	v_mov_b32_e32 v1, v175
	v_mov_b32_e32 v2, v175
	v_mov_b32_e32 v3, v175
	v_mov_b32_e32 v4, v175
	v_mov_b32_e32 v5, v175
	v_mov_b32_e32 v6, v175
	v_mov_b32_e32 v7, v175
	v_mov_b32_e32 v8, v175
	v_mov_b32_e32 v9, v175
	v_mov_b32_e32 v10, v175
	v_mov_b32_e32 v11, v175
	v_mov_b32_e32 v12, v175
	v_mov_b32_e32 v13, v175
	v_mov_b32_e32 v14, v175
	v_mov_b32_e32 v15, v175
	v_mov_b32_e32 v16, 0
	v_mov_b32_e32 v17, v175
	v_mov_b32_e32 v18, v175
	v_mov_b32_e32 v19, v175
	v_mov_b32_e32 v20, v175
	v_mov_b32_e32 v21, v175
	v_mov_b32_e32 v22, v175
	v_mov_b32_e32 v23, v175
	v_mov_b32_e32 v24, v175
	v_mov_b32_e32 v25, v175
	v_mov_b32_e32 v26, v175
	v_mov_b32_e32 v27, v175
	v_mov_b32_e32 v28, v175
	v_mov_b32_e32 v29, v175
	v_mov_b32_e32 v30, v175
	v_mov_b32_e32 v31, v175
	s_nop 15
	s_nop 7
	s_waitcnt lgkmcnt(0)
	s_barrier
	v_readfirstlane_b32 s93, v254
	s_cmpk_gt_u32 s93, 0xff
	s_cbranch_scc1 .LBB0_776
	s_and_b32 s10, s69, 6
	s_cmp_lg_u32 s10, 0
	s_cbranch_scc1 .Lmla_nomax1
	v_max3_f32 v96, v48, v49, v50
	v_max3_f32 v99, v32, v33, v34
	v_max3_f32 v98, v51, v52, v53
	v_max3_f32 v252, v35, v36, v37
	s_and_b32 s14, s69, 56
	v_max3_f32 v96, v96, v54, v55
	v_max3_f32 v99, v99, v38, v39
	v_max3_f32 v98, v98, v56, v57
	v_max3_f32 v252, v252, v40, v41
	s_cmp_eq_u32 s14, 0
	v_max3_f32 v96, v96, v58, v59
	v_max3_f32 v99, v99, v42, v43
	v_max3_f32 v98, v98, v60, v61
	v_max3_f32 v252, v252, v44, v45
	s_cselect_b64 s[10:11], -1, 0
	v_max3_f32 v96, v96, v62, v63
	v_max3_f32 v99, v99, v46, v47
	s_cmp_lg_u32 s14, 0
	v_max3_f32 v96, v96, v98, v99
	s_nop 0
	v_max_f32_e32 v96, v96, v252
	s_nop 0
	v_mov_b32_e32 v98, v96
	s_nop 1
	v_permlane32_swap_b32_e32 v96, v98
	v_max_f32_e32 v98, v98, v98
	v_max_f32_e32 v96, v96, v96
	v_max_f32_e32 v96, v96, v98
	v_cmp_lt_f32_e32 vcc, s54, v96
	v_mov_b32_e32 v98, 0
	s_cbranch_scc1 .Lmla_mx2
	v_cmp_gt_f32_e64 s[14:15], s55, v96
	s_cmp_lg_u64 s[14:15], 0
	s_cselect_b64 s[14:15], -1, 0
	v_cndmask_b32_e64 v98, 0, 1, s[14:15]

; #define ATT_SUMPACK(j) do { const float e0_ = (j) < 8 ? P0[2 * ((j) & 7)] : P1[2 * ((j) & 7)], e1_ = (j) < 8 ? P0[2 * ((j) & 7) + 1] : P1[2 * ((j) & 7) + 1]; \
;         if ((j) & 1) { rc += e0_; rd += e1_; } else { ra += e0_; rb += e1_; } S.pw[j] = cvtpk(e0_, e1_); } while (0)
; template <int GRP, bool has_next> __device__ __forceinline__ void att_step(const AttCtx<GRP>& C, AttState<GRP>& S, int s, f32x16& P0, f32x16& P1, f32x16& PN0, f32x16& PN1, u32x4& kreg, u32x4& preg, u32x4& vreg) {
;     ...
;     for (int c = 1; c < NKS; ++c) {
;         if (has_next) {
;             if (c == NK0) att_kfrag<GRP, NK0, NK1>(C, (s + 1) & 1, kfb);
;             const bf16x8 a0 = c < NK0 ? kfa[2 * c] : kfb[2 * (c - NK0)], a1 = c < NK0 ? kfa[2 * c + 1] : kfb[2 * (c - NK0) + 1];
;             PN0 = __builtin_amdgcn_mfma_f32_32x32x16_bf16(a0, S.qr[c], PN0, 0, 0, 0); PN1 = __builtin_amdgcn_mfma_f32_32x32x16_bf16(a1, S.qr[c], PN1, 0, 0, 0);
;         }
; #pragma unroll
;         for (int j = (c - 1) * 16 / NE; j < c * 16 / NE; ++j) {
;             if (j < 8) { P0[2 * j] = __builtin_amdgcn_exp2f(P0[2 * j]); P0[2 * j + 1] = __builtin_amdgcn_exp2f(P0[2 * j + 1]); }
;             else { P1[2 * (j - 8)] = __builtin_amdgcn_exp2f(P1[2 * (j - 8)]); P1[2 * (j - 8) + 1] = __builtin_amdgcn_exp2f(P1[2 * (j - 8) + 1]); }
;         }
;         if (c > 1) {
; #pragma unroll
;             for (int j = (c - 2) * 16 / NE; j < (c - 1) * 16 / NE; ++j) ATT_SUMPACK(j);
;         }
;         __builtin_amdgcn_sched_barrier(0);
;     }
;     if (has_next && S.refnz && t != 63) { PN0 = __builtin_amdgcn_mfma_f32_32x32x16_bf16(ones, qx, PN0, 0, 0, 0); PN1 = __builtin_amdgcn_mfma_f32_32x32x16_bf16(ones, qx, PN1, 0, 0, 0); }
.Lmla_nomax1:
	v_exp_f32_e32 v48, v48
	v_exp_f32_e32 v49, v49
	v_exp_f32_e32 v50, v50
	v_exp_f32_e32 v51, v51
	v_cvt_pk_bf16_f32 v216, v48, v49
	v_exp_f32_e32 v52, v52
	v_exp_f32_e32 v53, v53
	v_cvt_pk_bf16_f32 v217, v50, v51
	v_exp_f32_e32 v54, v54
	v_exp_f32_e32 v55, v55
	v_add_f32_e32 v248, v48, v52
	v_add_f32_e32 v249, v49, v53
	v_cvt_pk_bf16_f32 v218, v52, v53
	v_exp_f32_e32 v56, v56
	v_exp_f32_e32 v57, v57
	v_add_f32_e32 v250, v50, v54
	v_add_f32_e32 v251, v51, v55
	v_cvt_pk_bf16_f32 v219, v54, v55
	v_exp_f32_e32 v58, v58
	v_exp_f32_e32 v59, v59
	v_add_f32_e32 v248, v248, v56
	v_add_f32_e32 v249, v249, v57
	v_cvt_pk_bf16_f32 v220, v56, v57
	v_exp_f32_e32 v60, v60
	v_exp_f32_e32 v61, v61
	v_add_f32_e32 v250, v250, v58
	v_add_f32_e32 v251, v251, v59
	v_cvt_pk_bf16_f32 v221, v58, v59
	v_exp_f32_e32 v62, v62
	v_exp_f32_e32 v63, v63
	v_add_f32_e32 v248, v248, v60
	v_add_f32_e32 v249, v249, v61
	v_cvt_pk_bf16_f32 v222, v60, v61
	v_exp_f32_e32 v32, v32
	v_exp_f32_e32 v33, v33
	v_add_f32_e32 v250, v250, v62
	v_add_f32_e32 v251, v251, v63
	v_cvt_pk_bf16_f32 v223, v62, v63
	v_exp_f32_e32 v34, v34
	v_exp_f32_e32 v35, v35
	v_add_f32_e32 v248, v248, v32
	v_add_f32_e32 v249, v249, v33
	v_cvt_pk_bf16_f32 v224, v32, v33
	v_exp_f32_e32 v36, v36
	v_exp_f32_e32 v37, v37
	v_add_f32_e32 v250, v250, v34
	v_add_f32_e32 v251, v251, v35
	v_cvt_pk_bf16_f32 v225, v34, v35
	v_exp_f32_e32 v38, v38
	v_exp_f32_e32 v39, v39
	v_add_f32_e32 v248, v248, v36
	v_add_f32_e32 v249, v249, v37
	v_cvt_pk_bf16_f32 v226, v36, v37
	v_exp_f32_e32 v40, v40
	v_exp_f32_e32 v41, v41
	v_add_f32_e32 v250, v250, v38
	v_add_f32_e32 v251, v251, v39
	v_cvt_pk_bf16_f32 v227, v38, v39
	v_exp_f32_e32 v42, v42
	v_exp_f32_e32 v43, v43
	v_add_f32_e32 v248, v248, v40
	v_add_f32_e32 v249, v249, v41
	v_cvt_pk_bf16_f32 v228, v40, v41
	v_exp_f32_e32 v44, v44
	v_exp_f32_e32 v45, v45
	v_add_f32_e32 v250, v250, v42
	v_add_f32_e32 v251, v251, v43
	v_cvt_pk_bf16_f32 v229, v42, v43
	v_exp_f32_e32 v46, v46
	v_exp_f32_e32 v47, v47
	v_add_f32_e32 v248, v248, v44
	v_add_f32_e32 v249, v249, v45
	v_cvt_pk_bf16_f32 v230, v44, v45
	v_add_f32_e32 v250, v250, v46
	v_add_f32_e32 v251, v251, v47
	v_cvt_pk_bf16_f32 v231, v46, v47
	v_add_f32_e32 v248, v248, v249
	v_add_f32_e32 v250, v250, v251
	v_add_f32_e32 v248, v248, v250
	v_add_f32_e32 v170, v170, v248
.Lmla_L_loop:
	ds_read_b128 v[136:139], v174 offset:13312
	ds_read_b128 v[140:143], v174 offset:19968
	ds_read_b128 v[144:147], v174 offset:13344
	ds_read_b128 v[148:151], v174 offset:20000
	ds_read_b128 v[176:179], v174 offset:13376
	ds_read_b128 v[180:183], v174 offset:20032
	s_waitcnt lgkmcnt(5)
	v_mfma_f32_32x32x16_bf16 v[80:95], v[136:139], v[128:131], 0
	ds_read_b128 v[136:139], v174 offset:13408
	s_waitcnt lgkmcnt(5)
	v_mfma_f32_32x32x16_bf16 v[64:79], v[140:143], v[128:131], 0
	ds_read_b128 v[140:143], v174 offset:20064
	s_waitcnt lgkmcnt(5)
	v_mfma_f32_32x32x16_bf16 v[80:95], v[144:147], v[124:127], v[80:95]
	ds_read_b128 v[144:147], v174 offset:13440
	s_waitcnt lgkmcnt(5)
	v_mfma_f32_32x32x16_bf16 v[64:79], v[148:151], v[124:127], v[64:79]
	ds_read_b128 v[148:151], v174 offset:20096
	s_waitcnt lgkmcnt(5)
	v_mfma_f32_32x32x16_bf16 v[80:95], v[176:179], v[120:123], v[80:95]
	ds_read_b128 v[176:179], v174 offset:13472
	s_waitcnt lgkmcnt(5)
	v_mfma_f32_32x32x16_bf16 v[64:79], v[180:183], v[120:123], v[64:79]
	ds_read_b128 v[180:183], v174 offset:20128
	s_waitcnt lgkmcnt(5)
	v_mfma_f32_32x32x16_bf16 v[80:95], v[136:139], v[116:119], v[80:95]
	ds_read_b128 v[232:235], v157 offset:26624
	s_waitcnt lgkmcnt(5)
	v_mfma_f32_32x32x16_bf16 v[64:79], v[140:143], v[116:119], v[64:79]
	ds_read_b128 v[236:239], v157 offset:31232
	s_waitcnt lgkmcnt(5)
	v_mfma_f32_32x32x16_bf16 v[80:95], v[144:147], v[112:115], v[80:95]
	ds_read_b128 v[240:243], v157 offset:26656
	s_waitcnt lgkmcnt(5)
	v_mfma_f32_32x32x16_bf16 v[64:79], v[148:151], v[112:115], v[64:79]
	ds_read_b128 v[244:247], v157 offset:31264
	s_waitcnt lgkmcnt(5)
	v_mfma_f32_32x32x16_bf16 v[80:95], v[176:179], v[108:111], v[80:95]
	s_waitcnt lgkmcnt(4)
	v_mfma_f32_32x32x16_bf16 v[64:79], v[180:183], v[108:111], v[64:79]
	s_cmp_eq_u32 s72, 0
	s_cbranch_scc1 .Lmla_nrz3
	v_xor_b32_e32 v195, 0x80000000, v175
	s_mov_b32 s18, s16
	s_mov_b32 s19, s16
	s_mov_b32 s17, s16
	v_mov_b64_e32 v[186:187], s[18:19]
	v_mov_b64_e32 v[184:185], s[16:17]
	s_mov_b64 vcc, s[0:1]
	v_cndmask_b32_sdwa v96, v97, v195, vcc dst_sel:DWORD dst_unused:UNUSED_PAD src0_sel:DWORD src1_sel:WORD_1
	v_mov_b32_e32 v98, v97
	v_mov_b32_e32 v99, v97
	s_nop 1
	v_mfma_f32_32x32x16_bf16 v[80:95], v[184:187], v[96:99], v[80:95]
	v_mfma_f32_32x32x16_bf16 v[64:79], v[184:187], v[96:99], v[64:79]
; #define ATT_BAR() do { __builtin_amdgcn_sched_barrier(0); asm volatile("s_waitcnt lgkmcnt(0)\n\ts_barrier" ::: "memory"); __builtin_amdgcn_sched_barrier(0); } while (0)
; #define ATT_SUMPACK(j) do { const float e0_ = (j) < 8 ? P0[2 * ((j) & 7)] : P1[2 * ((j) & 7)], e1_ = (j) < 8 ? P0[2 * ((j) & 7) + 1] : P1[2 * ((j) & 7) + 1]; \
;         if ((j) & 1) { rc += e0_; rd += e1_; } else { ra += e0_; rb += e1_; } S.pw[j] = cvtpk(e0_, e1_); } while (0)
; template <int GRP, bool has_next> __device__ __forceinline__ void att_step(const AttCtx<GRP>& C, AttState<GRP>& S, int s, f32x16& P0, f32x16& P1, f32x16& PN0, f32x16& PN1, u32x4& kreg, u32x4& preg, u32x4& vreg) {
;     ...
;         if (t == 63) {
; #pragma unroll
;             for (int ks = 0; ks < NKS; ++ks) S.qr[ks] = *(const bf16x8*)(C.Q + C.qrow * QP + (h + 1) * DK + ks * 16 + C.hi * 8);
;         }
;     ...
;     att_vfrag<GRP>(C, s & 1, vf);
; #pragma unroll
;     for (int j = (NE - 1) * 16 / NE; j < 16; ++j) ATT_SUMPACK(j);
;     ...
;     S.lrun += (ra + rb) + (rc + rd);
;     att_pv<GRP>(S, vf);
;     if (t == 63) {
;         att_finish_head<GRP>(C, S, h);
;         S.o0 = (f32x16){}; S.o1 = (f32x16){}; S.lrun = 0.f; S.mhat = 0.f; S.refnz = 0;
;     }
;     att_stld<GRP>(C, s, kreg, preg, vreg);
;     ATT_BAR();
.Lmla_nrz3:
	s_waitcnt lgkmcnt(3)
	v_mfma_f32_32x32x16_bf16 v[0:15], v[232:235], v[216:219], v[0:15]
	ds_read_b128 v[232:235], v157 offset:26688
	s_waitcnt lgkmcnt(3)
	v_mfma_f32_32x32x16_bf16 v[16:31], v[236:239], v[216:219], v[16:31]
	ds_read_b128 v[236:239], v157 offset:31296
	s_waitcnt lgkmcnt(3)
	v_mfma_f32_32x32x16_bf16 v[0:15], v[240:243], v[220:223], v[0:15]
	ds_read_b128 v[240:243], v157 offset:26720
	s_waitcnt lgkmcnt(3)
	v_mfma_f32_32x32x16_bf16 v[16:31], v[244:247], v[220:223], v[16:31]
	ds_read_b128 v[244:247], v157 offset:31328
	s_waitcnt lgkmcnt(3)
	v_mfma_f32_32x32x16_bf16 v[0:15], v[232:235], v[224:227], v[0:15]
	s_waitcnt lgkmcnt(2)
	v_mfma_f32_32x32x16_bf16 v[16:31], v[236:239], v[224:227], v[16:31]
	s_waitcnt lgkmcnt(1)
	v_mfma_f32_32x32x16_bf16 v[0:15], v[240:243], v[228:231], v[0:15]
	s_waitcnt lgkmcnt(0)
	v_mfma_f32_32x32x16_bf16 v[16:31], v[244:247], v[228:231], v[16:31]
	s_waitcnt vmcnt(1)
	ds_write_b128 v171, v[104:107]
	ds_write_b128 v172, v[100:103] offset:128
	s_mov_b32 s84, 0xfe000000
	s_mov_b32 s85, -1
	s_waitcnt vmcnt(0)
	ds_write_b128 v169, v[132:135] offset:35840
	v_lshl_add_u64 v[192:193], v[166:167], 0, s[84:85]
	s_add_i32 s14, s67, 0xfffff800
	s_and_b32 s14, s14, 0x1f800
	s_lshl_b32 s62, s14, 1
	global_load_dwordx4 v[104:107], v[192:193], off
	v_lshl_add_u64 v[190:191], v[160:161], 0, s[62:63]
	global_load_dwordx4 v[100:103], v[190:191], off
	s_mov_b32 s84, 0xffffe000
	s_nop 0
	v_lshl_add_u64 v[192:193], v[166:167], 0, s[84:85]
	global_load_dwordx4 v[132:135], v[192:193], off
	v_exp_f32_e32 v80, v80
	v_exp_f32_e32 v81, v81
	v_exp_f32_e32 v82, v82
	v_exp_f32_e32 v83, v83
	v_cvt_pk_bf16_f32 v216, v80, v81
	v_exp_f32_e32 v84, v84
	v_exp_f32_e32 v85, v85
	v_cvt_pk_bf16_f32 v217, v82, v83
	v_exp_f32_e32 v86, v86
	v_exp_f32_e32 v87, v87
	v_add_f32_e32 v248, v80, v84
	v_add_f32_e32 v249, v81, v85
	v_cvt_pk_bf16_f32 v218, v84, v85
	v_exp_f32_e32 v88, v88
	v_exp_f32_e32 v89, v89
	v_add_f32_e32 v250, v82, v86
	v_add_f32_e32 v251, v83, v87
	v_cvt_pk_bf16_f32 v219, v86, v87
	v_exp_f32_e32 v90, v90
	v_exp_f32_e32 v91, v91
	v_add_f32_e32 v248, v248, v88
	v_add_f32_e32 v249, v249, v89
	v_cvt_pk_bf16_f32 v220, v88, v89
	v_exp_f32_e32 v92, v92
	v_exp_f32_e32 v93, v93
	v_add_f32_e32 v250, v250, v90
	v_add_f32_e32 v251, v251, v91
	v_cvt_pk_bf16_f32 v221, v90, v91
	v_exp_f32_e32 v94, v94
	v_exp_f32_e32 v95, v95
	v_add_f32_e32 v248, v248, v92
	v_add_f32_e32 v249, v249, v93
	v_cvt_pk_bf16_f32 v222, v92, v93
	v_exp_f32_e32 v64, v64
	v_exp_f32_e32 v65, v65
	v_add_f32_e32 v250, v250, v94
	v_add_f32_e32 v251, v251, v95
	v_cvt_pk_bf16_f32 v223, v94, v95
	v_exp_f32_e32 v66, v66
	v_exp_f32_e32 v67, v67
	v_add_f32_e32 v248, v248, v64
	v_add_f32_e32 v249, v249, v65
	v_cvt_pk_bf16_f32 v224, v64, v65
	v_exp_f32_e32 v68, v68
	v_exp_f32_e32 v69, v69
	v_add_f32_e32 v250, v250, v66
	v_add_f32_e32 v251, v251, v67
	v_cvt_pk_bf16_f32 v225, v66, v67
	v_exp_f32_e32 v70, v70
	v_exp_f32_e32 v71, v71
	v_add_f32_e32 v248, v248, v68
	v_add_f32_e32 v249, v249, v69
	v_cvt_pk_bf16_f32 v226, v68, v69
	v_exp_f32_e32 v72, v72
	v_exp_f32_e32 v73, v73
	v_add_f32_e32 v250, v250, v70
	v_add_f32_e32 v251, v251, v71
	v_cvt_pk_bf16_f32 v227, v70, v71
	v_exp_f32_e32 v74, v74
	v_exp_f32_e32 v75, v75
	v_add_f32_e32 v248, v248, v72
	v_add_f32_e32 v249, v249, v73
	v_cvt_pk_bf16_f32 v228, v72, v73
	v_exp_f32_e32 v76, v76
	v_exp_f32_e32 v77, v77
	v_add_f32_e32 v250, v250, v74
	v_add_f32_e32 v251, v251, v75
	v_cvt_pk_bf16_f32 v229, v74, v75
	v_exp_f32_e32 v78, v78
	v_exp_f32_e32 v79, v79
	v_add_f32_e32 v248, v248, v76
	v_add_f32_e32 v249, v249, v77
	v_cvt_pk_bf16_f32 v230, v76, v77
	v_add_f32_e32 v250, v250, v78
	v_add_f32_e32 v251, v251, v79
	v_cvt_pk_bf16_f32 v231, v78, v79
	v_add_f32_e32 v248, v248, v249
	v_add_f32_e32 v250, v250, v251
	v_add_f32_e32 v248, v248, v250
	v_add_f32_e32 v170, v170, v248
	s_waitcnt lgkmcnt(0)
	s_barrier
	s_add_i32 s62, s69, 1
	s_lshr_b32 s71, s69, 6
	s_add_i32 s71, s71, s60
	s_and_b32 s10, s62, 63
	s_cmp_eq_u32 s10, 63
	s_cselect_b64 s[86:87], -1, 0
	s_cmp_lg_u64 s[86:87], 0
	s_cbranch_scc0 .Lmla_noq5
	s_mul_i32 s18, s71, 0x60
	s_ashr_i32 s19, s18, 31
	v_lshl_add_u64 v[192:193], s[18:19], 1, v[164:165]
	global_load_dwordx4 v[128:131], v[192:193], off offset:192
	global_load_dwordx4 v[124:127], v[192:193], off offset:224
	global_load_dwordx4 v[120:123], v[192:193], off offset:256
	global_load_dwordx4 v[116:119], v[192:193], off offset:288
	global_load_dwordx4 v[112:115], v[192:193], off offset:320
	global_load_dwordx4 v[108:111], v[192:193], off offset:352
	s_waitcnt vmcnt(0)
; __device__ __forceinline__ float max2f(float a, float b) { float r; asm("v_max_f32_e32 %0, %1, %2" : "=v"(r) : "v"(a), "v"(b)); return r; }
; template <int GRP, bool has_next> __device__ __forceinline__ void att_step(const AttCtx<GRP>& C, AttState<GRP>& S, int s, f32x16& P0, f32x16& P1, f32x16& PN0, f32x16& PN1, u32x4& kreg, u32x4& preg, u32x4& vreg) {
;     ...
;         att_kfrag<GRP, 0, NK0>(C, (s + 1) & 1, kfa);
;     }
;     if (has_next) { PN0 = __builtin_amdgcn_mfma_f32_32x32x16_bf16(kfa[0], S.qr[0], (f32x16){}, 0, 0, 0); PN1 = __builtin_amdgcn_mfma_f32_32x32x16_bf16(kfa[1], S.qr[0], (f32x16){}, 0, 0, 0); }
;     if ((t & 7) == 0) {
;         float ma = max3f(P0[0], P0[1], P0[2]), mb = max3f(P0[3], P0[4], P0[5]), mc = max3f(P1[0], P1[1], P1[2]), md = max3f(P1[3], P1[4], P1[5]);
;         ma = max3f(ma, P0[6], P0[7]); mb = max3f(mb, P0[8], P0[9]); mc = max3f(mc, P1[6], P1[7]); md = max3f(md, P1[8], P1[9]);
;         ma = max3f(ma, P0[10], P0[11]); mb = max3f(mb, P0[12], P0[13]); mc = max3f(mc, P1[10], P1[11]); md = max3f(md, P1[12], P1[13]);
;         ma = max3f(ma, P0[14], P0[15]); mc = max3f(mc, P1[14], P1[15]); ma = max3f(ma, mb, mc); mb = md;
;         const float mx = xhalf_max(max2f(ma, mb));
;         const int up = __any(mx > THR), dn = (t == 0) ? __any(mx < -THR) : 0;
;         if (up | dn) {
;             const float dl = ceilf((t == 0) ? mx : fmaxf(mx, 0.f));
;             const float f = (t == 0) ? 0.f : __builtin_amdgcn_exp2f(-dl);
;             S.mhat += dl; S.lrun *= f;
; #pragma unroll
;             for (int r = 0; r < 16; ++r) { P0[r] -= dl; P1[r] -= dl; S.o0[r] *= f; S.o1[r] *= f; }
;             S.refnz = __any(S.mhat != 0.f);
;         }
;     }
;     __builtin_amdgcn_sched_barrier(0);
;     const unsigned mbits = (t == 63 || C.hi != 0) ? 0u : (__float_as_uint(-S.mhat) >> 16);
;     const u32x4 qxw = {mbits, 0u, 0u, 0u}; const bf16x8 qx = __builtin_bit_cast(bf16x8, qxw);
;     const bf16x8 ones = {0x3f80, 0x3f80, 0x3f80, 0x3f80, 0x3f80, 0x3f80, 0x3f80, 0x3f80};
;     constexpr int NE = NKS - 1;
;     float ra = 0.f, rb = 0.f, rc = 0.f, rd = 0.f;
;     ...
; #pragma unroll
;     for (int c = 1; c < NKS; ++c) {
;         if (has_next) {
;             if (c == NK0) att_kfrag<GRP, NK0, NK1>(C, (s + 1) & 1, kfb);
;             const bf16x8 a0 = c < NK0 ? kfa[2 * c] : kfb[2 * (c - NK0)], a1 = c < NK0 ? kfa[2 * c + 1] : kfb[2 * (c - NK0) + 1];
.Lmla_noq5:
	ds_read_b128 v[136:139], v174 offset:0
	ds_read_b128 v[140:143], v174 offset:6656
	ds_read_b128 v[144:147], v174 offset:32
	ds_read_b128 v[148:151], v174 offset:6688
	ds_read_b128 v[176:179], v174 offset:64
	ds_read_b128 v[180:183], v174 offset:6720
	s_waitcnt lgkmcnt(5)
	v_mfma_f32_32x32x16_bf16 v[48:63], v[136:139], v[128:131], 0
	ds_read_b128 v[136:139], v174 offset:96
	s_waitcnt lgkmcnt(5)
	v_mfma_f32_32x32x16_bf16 v[32:47], v[140:143], v[128:131], 0
	ds_read_b128 v[140:143], v174 offset:6752
	s_waitcnt lgkmcnt(5)
	v_mfma_f32_32x32x16_bf16 v[48:63], v[144:147], v[124:127], v[48:63]
	ds_read_b128 v[144:147], v174 offset:128
	s_waitcnt lgkmcnt(5)
	v_mfma_f32_32x32x16_bf16 v[32:47], v[148:151], v[124:127], v[32:47]
	ds_read_b128 v[148:151], v174 offset:6784
	s_waitcnt lgkmcnt(5)
	v_mfma_f32_32x32x16_bf16 v[48:63], v[176:179], v[120:123], v[48:63]
	ds_read_b128 v[176:179], v174 offset:160
	s_waitcnt lgkmcnt(5)
	v_mfma_f32_32x32x16_bf16 v[32:47], v[180:183], v[120:123], v[32:47]
	ds_read_b128 v[180:183], v174 offset:6816
	s_waitcnt lgkmcnt(5)
	v_mfma_f32_32x32x16_bf16 v[48:63], v[136:139], v[116:119], v[48:63]
	ds_read_b128 v[232:235], v157 offset:35840
	s_waitcnt lgkmcnt(5)
	v_mfma_f32_32x32x16_bf16 v[32:47], v[140:143], v[116:119], v[32:47]
	ds_read_b128 v[236:239], v157 offset:40448
	s_waitcnt lgkmcnt(5)
	v_mfma_f32_32x32x16_bf16 v[48:63], v[144:147], v[112:115], v[48:63]
	ds_read_b128 v[240:243], v157 offset:35872
	s_waitcnt lgkmcnt(5)
	v_mfma_f32_32x32x16_bf16 v[32:47], v[148:151], v[112:115], v[32:47]
	ds_read_b128 v[244:247], v157 offset:40480
	s_waitcnt lgkmcnt(5)
	v_mfma_f32_32x32x16_bf16 v[48:63], v[176:179], v[108:111], v[48:63]
	s_waitcnt lgkmcnt(4)
	v_mfma_f32_32x32x16_bf16 v[32:47], v[180:183], v[108:111], v[32:47]
	s_cmp_eq_u32 s72, 0
	s_cbranch_scc1 .Lmla_nrz6
	s_cmp_lg_u64 s[86:87], 0
	s_cbranch_scc1 .Lmla_nrz6
	v_xor_b32_e32 v195, 0x80000000, v175
	s_mov_b32 s18, s16
	s_mov_b32 s19, s16
	s_mov_b32 s17, s16
	v_mov_b64_e32 v[186:187], s[18:19]
	v_mov_b64_e32 v[184:185], s[16:17]
	s_mov_b64 vcc, s[0:1]
	v_cndmask_b32_sdwa v96, v97, v195, vcc dst_sel:DWORD dst_unused:UNUSED_PAD src0_sel:DWORD src1_sel:WORD_1
	v_mov_b32_e32 v98, v97
	v_mov_b32_e32 v99, v97
	s_nop 1
	v_mfma_f32_32x32x16_bf16 v[48:63], v[184:187], v[96:99], v[48:63]
	v_mfma_f32_32x32x16_bf16 v[32:47], v[184:187], v[96:99], v[32:47]
.Lmla_nrz6:
	s_waitcnt lgkmcnt(3)
	v_mfma_f32_32x32x16_bf16 v[0:15], v[232:235], v[216:219], v[0:15]
	ds_read_b128 v[232:235], v157 offset:35904
	s_waitcnt lgkmcnt(3)
	v_mfma_f32_32x32x16_bf16 v[16:31], v[236:239], v[216:219], v[16:31]
	ds_read_b128 v[236:239], v157 offset:40512
	s_waitcnt lgkmcnt(3)
	v_mfma_f32_32x32x16_bf16 v[0:15], v[240:243], v[220:223], v[0:15]
	ds_read_b128 v[240:243], v157 offset:35936
	s_waitcnt lgkmcnt(3)
	v_mfma_f32_32x32x16_bf16 v[16:31], v[244:247], v[220:223], v[16:31]
	ds_read_b128 v[244:247], v157 offset:40544
	s_waitcnt lgkmcnt(3)
	v_mfma_f32_32x32x16_bf16 v[0:15], v[232:235], v[224:227], v[0:15]
	s_waitcnt lgkmcnt(2)
	v_mfma_f32_32x32x16_bf16 v[16:31], v[236:239], v[224:227], v[16:31]
	s_waitcnt lgkmcnt(1)
	v_mfma_f32_32x32x16_bf16 v[0:15], v[240:243], v[228:231], v[0:15]
	s_waitcnt lgkmcnt(0)
	v_mfma_f32_32x32x16_bf16 v[16:31], v[244:247], v[228:231], v[16:31]
	s_cmp_lg_u64 s[86:87], 0
	s_cbranch_scc0 .Lmla_nofin7
; #define LAS __attribute__((address_space(3)))
; __device__ __forceinline__ unsigned cvtpk(float lo, float hi) { f32x2_t v = {lo, hi}; bf16x2_t b = __builtin_convertvector(v, bf16x2_t); return __builtin_bit_cast(unsigned, b); }
; __device__ __forceinline__ float xhalf_sum(float m) { auto rr = __builtin_amdgcn_permlane32_swap(__float_as_uint(m), __float_as_uint(m), false, false); return __uint_as_float(rr[0]) + __uint_as_float(rr[1]); }
; template <int GRP> __device__ __forceinline__ void att_stk(const AttCtx<GRP>& C, int buf, const u32x4& kreg, const u32x4& preg) {
;     *(LAS u32x4*)(C.lds + buf * KBUF + C.kwo) = kreg; if (GRP == 0 && C.tid < 256) *(LAS u32x4*)(C.lds + buf * KBUF + C.pwo) = preg;
; }
; template <int GRP> __device__ __forceinline__ void att_stld(const AttCtx<GRP>& C, int s, u32x4& kreg, u32x4& preg, u32x4& vreg) {
;     constexpr int NSTEP = 256;
;     if (s + 2 < NSTEP) att_stk<GRP>(C, s & 1, kreg, preg);
;     if (s + 1 < NSTEP) att_stv<GRP>(C, (s + 1) & 1, vreg);
;     if (s + 3 < NSTEP) att_ldk<GRP>(C, s + 3, kreg, preg);
;     if (s + 2 < NSTEP) att_ldv<GRP>(C, s + 2, vreg);
; }
; template <int GRP> __device__ __forceinline__ void att_finish_head(const AttCtx<GRP>& C, AttState<GRP>& S, int h) {
;     const float inv = 1.0f / xhalf_sum(S.lrun);
;     bf16_t* orow = C.O + C.qrow * 1024 + GRP * 512 + h * 64 + 4 * C.hi;
; #pragma unroll
;     for (int rr = 0; rr < 4; ++rr) {
;         const f32x4 v0 = (f32x4){S.o0[4 * rr], S.o0[4 * rr + 1], S.o0[4 * rr + 2], S.o0[4 * rr + 3]} * inv, v1 = (f32x4){S.o1[4 * rr], S.o1[4 * rr + 1], S.o1[4 * rr + 2], S.o1[4 * rr + 3]} * inv;
;         S.ssq += (v0[0] * v0[0] + v0[1] * v0[1]) + (v0[2] * v0[2] + v0[3] * v0[3]) + (v1[0] * v1[0] + v1[1] * v1[1]) + (v1[2] * v1[2] + v1[3] * v1[3]);
;         u32x2 s0, s1; s0.x = cvtpk(v0[0], v0[1]); s0.y = cvtpk(v0[2], v0[3]); s1.x = cvtpk(v1[0], v1[1]); s1.y = cvtpk(v1[2], v1[3]);
;         *(u32x2*)(orow + 8 * rr) = s0; *(u32x2*)(orow + 32 + 8 * rr) = s1;
;     }
; }
	s_nop 7
	s_nop 3
	v_mov_b32_e32 v64, v170
	s_nop 1
	v_permlane32_swap_b32_e32 v170, v64
	v_add_f32_e32 v64, v170, v64
	v_div_scale_f32 v65, s[10:11], v64, v64, 1.0
	v_rcp_f32_e32 v66, v65
	s_lshl_b32 s10, s71, 6
	s_ashr_i32 s11, s10, 31
	v_mov_b32_e32 v175, 0
	v_fma_f32 v67, -v65, v66, 1.0
	v_fmac_f32_e32 v66, v67, v66
	v_div_scale_f32 v67, vcc, 1.0, v64, 1.0
	v_mul_f32_e32 v68, v67, v66
	v_fma_f32 v69, -v65, v68, v67
	v_fmac_f32_e32 v68, v69, v66
	v_fma_f32 v65, -v65, v68, v67
	v_div_fmas_f32 v65, v65, v66, v68
	v_div_fixup_f32 v64, v65, v64, 1.0
	v_pk_mul_f32 v[0:1], v[0:1], v[64:65] op_sel_hi:[1,0]
	v_pk_mul_f32 v[2:3], v[2:3], v[64:65] op_sel_hi:[1,0]
	v_pk_mul_f32 v[70:71], v[0:1], v[0:1]
	v_pk_mul_f32 v[68:69], v[2:3], v[2:3]
	v_pk_mul_f32 v[16:17], v[16:17], v[64:65] op_sel_hi:[1,0]
	v_pk_mul_f32 v[18:19], v[18:19], v[64:65] op_sel_hi:[1,0]
	v_pk_mov_b32 v[72:73], v[70:71], v[68:69] op_sel:[1,0]
	v_mov_b32_e32 v71, v69
	v_pk_add_f32 v[68:69], v[72:73], v[70:71]
	v_pk_mul_f32 v[70:71], v[18:19], v[18:19]
	v_pk_mul_f32 v[72:73], v[16:17], v[16:17]
	v_mov_b32_e32 v74, v70
	v_mov_b32_e32 v75, v72
	v_mov_b32_e32 v72, v71
	v_pk_add_f32 v[70:71], v[74:75], v[72:73]
	v_add_f32_e32 v65, v68, v69
	v_add_f32_e32 v65, v71, v65
	v_add_f32_e32 v65, v70, v65
	v_lshl_add_u64 v[66:67], s[10:11], 1, v[162:163]
	v_add_f32_e32 v65, v168, v65
	v_cvt_pk_bf16_f32 v0, v0, v1
	v_cvt_pk_bf16_f32 v1, v2, v3
	v_cvt_pk_bf16_f32 v2, v16, v17
	v_cvt_pk_bf16_f32 v3, v18, v19
	global_store_dwordx2 v[66:67], v[0:1], off
	global_store_dwordx2 v[66:67], v[2:3], off offset:64
	v_pk_mul_f32 v[0:1], v[4:5], v[64:65] op_sel_hi:[1,0]
	v_pk_mul_f32 v[2:3], v[6:7], v[64:65] op_sel_hi:[1,0]
	v_pk_mul_f32 v[4:5], v[20:21], v[64:65] op_sel_hi:[1,0]
	v_pk_mul_f32 v[6:7], v[22:23], v[64:65] op_sel_hi:[1,0]
	v_pk_mul_f32 v[16:17], v[2:3], v[2:3]
	v_pk_mul_f32 v[18:19], v[0:1], v[0:1]
	v_cvt_pk_bf16_f32 v0, v0, v1
	v_cvt_pk_bf16_f32 v1, v2, v3
	v_cvt_pk_bf16_f32 v2, v4, v5
	v_cvt_pk_bf16_f32 v3, v6, v7
	global_store_dwordx2 v[66:67], v[0:1], off offset:16
	global_store_dwordx2 v[66:67], v[2:3], off offset:80
	v_pk_mul_f32 v[2:3], v[8:9], v[64:65] op_sel_hi:[1,0]
	v_pk_mov_b32 v[20:21], v[18:19], v[16:17] op_sel:[1,0]
	v_mul_f32_e32 v8, v2, v2
	v_mov_b32_e32 v19, v17
	v_pk_mul_f32 v[0:1], v[10:11], v[64:65] op_sel_hi:[1,0]
	v_pk_fma_f32 v[8:9], v[2:3], v[2:3], v[8:9] op_sel_hi:[1,1,0]
	v_pk_add_f32 v[16:17], v[20:21], v[18:19]
	v_pk_mul_f32 v[18:19], v[6:7], v[6:7]
	v_pk_mul_f32 v[20:21], v[4:5], v[4:5]
	v_pk_mul_f32 v[4:5], v[26:27], v[64:65] op_sel_hi:[1,0]
	v_pk_mul_f32 v[6:7], v[24:25], v[64:65] op_sel_hi:[1,0]
	v_mul_f32_e32 v8, v0, v0
	v_pk_fma_f32 v[10:11], v[0:1], v[0:1], v[8:9] op_sel_hi:[1,1,0]
	v_cvt_pk_bf16_f32 v2, v2, v3
	v_cvt_pk_bf16_f32 v3, v0, v1
	v_cvt_pk_bf16_f32 v0, v6, v7
	v_cvt_pk_bf16_f32 v1, v4, v5
	v_mov_b32_e32 v22, v18
	v_mov_b32_e32 v23, v20
	v_mov_b32_e32 v20, v19
	global_store_dwordx2 v[66:67], v[2:3], off offset:32
	global_store_dwordx2 v[66:67], v[0:1], off offset:96
	v_pk_mul_f32 v[0:1], v[12:13], v[64:65] op_sel_hi:[1,0]
	v_pk_add_f32 v[18:19], v[22:23], v[20:21]
	v_pk_mul_f32 v[2:3], v[14:15], v[64:65] op_sel_hi:[1,0]
	v_mov_b32_e32 v21, v6
	v_mov_b32_e32 v6, v1
	v_mul_f32_e32 v8, v2, v2
	v_mul_f32_e32 v10, v3, v3
	v_mov_b32_e32 v20, v0
	v_pk_mul_f32 v[6:7], v[6:7], v[6:7]
	v_pk_add_f32 v[16:17], v[16:17], v[16:17] op_sel:[0,1] op_sel_hi:[1,0]
	v_pk_mul_f32 v[12:13], v[28:29], v[64:65] op_sel_hi:[1,0]
	v_pk_fma_f32 v[6:7], v[20:21], v[20:21], v[6:7]
	v_pk_add_f32 v[8:9], v[8:9], v[10:11]
	v_pk_add_f32 v[16:17], v[18:19], v[16:17] op_sel:[1,0] op_sel_hi:[0,1]
	v_pk_add_f32 v[6:7], v[6:7], v[8:9]
	v_mov_b32_e32 v9, v4
	v_mov_b32_e32 v4, v13
	v_pk_add_f32 v[16:17], v[18:19], v[16:17]
	v_pk_mul_f32 v[14:15], v[30:31], v[64:65] op_sel_hi:[1,0]
	v_mov_b32_e32 v8, v12
	v_pk_mul_f32 v[4:5], v[4:5], v[4:5]
	v_mul_f32_e32 v18, v14, v14
	v_mul_f32_e32 v64, v15, v15
	v_pk_fma_f32 v[4:5], v[8:9], v[8:9], v[4:5]
	v_mov_b32_e32 v19, v16
	v_pk_add_f32 v[4:5], v[4:5], v[6:7]
	v_pk_add_f32 v[6:7], v[18:19], v[64:65]
	v_cvt_pk_bf16_f32 v0, v0, v1
	v_pk_add_f32 v[4:5], v[4:5], v[6:7]
	v_cvt_pk_bf16_f32 v1, v2, v3
	v_cvt_pk_bf16_f32 v2, v12, v13
	v_cvt_pk_bf16_f32 v3, v14, v15
	v_add_f32_e32 v168, v4, v5
	global_store_dwordx2 v[66:67], v[0:1], off offset:48
	global_store_dwordx2 v[66:67], v[2:3], off offset:112
	s_mov_b32 s72, 0
	v_mov_b32_e32 v170, 0
	v_mov_b32_e32 v0, 0
	v_mov_b32_e32 v1, v175
	v_mov_b32_e32 v2, v175
	v_mov_b32_e32 v3, v175
	v_mov_b32_e32 v4, v175
	v_mov_b32_e32 v5, v175
	v_mov_b32_e32 v6, v175
	v_mov_b32_e32 v7, v175
	v_mov_b32_e32 v8, v175
	v_mov_b32_e32 v9, v175
	v_mov_b32_e32 v10, v175
	v_mov_b32_e32 v11, v175
	v_mov_b32_e32 v12, v175
	v_mov_b32_e32 v13, v175
	v_mov_b32_e32 v14, v175
	v_mov_b32_e32 v15, v175
	v_mov_b32_e32 v16, 0
	v_mov_b32_e32 v17, v175
	v_mov_b32_e32 v18, v175
	v_mov_b32_e32 v19, v175
	v_mov_b32_e32 v20, v175
	v_mov_b32_e32 v21, v175
	v_mov_b32_e32 v22, v175
	v_mov_b32_e32 v23, v175
	v_mov_b32_e32 v24, v175
	v_mov_b32_e32 v25, v175
	v_mov_b32_e32 v26, v175
	v_mov_b32_e32 v27, v175
	v_mov_b32_e32 v28, v175
	v_mov_b32_e32 v29, v175
	v_mov_b32_e32 v30, v175
	v_mov_b32_e32 v31, v175
.Lmla_nofin7:
	s_waitcnt vmcnt(1)
	ds_write_b128 v171, v[104:107] offset:13312
	ds_write_b128 v172, v[100:103] offset:13440
	s_waitcnt vmcnt(0)
	ds_write_b128 v173, v[132:135] offset:26624
	s_cmpk_gt_u32 s62, 0xfc
	s_cbranch_scc1 .Lmla_nold8
	s_mov_b32 s88, s70
	s_ashr_i32 s89, s70, 31
	v_lshl_add_u64 v[192:193], s[88:89], 1, v[158:159]
	s_and_b32 s14, s67, 0x1f000
	s_lshl_b32 s14, s14, 1
	s_mov_b32 s15, 0
	global_load_dwordx4 v[104:107], v[192:193], off
	v_lshl_add_u64 v[190:191], v[160:161], 0, s[14:15]
	global_load_dwordx4 v[100:103], v[190:191], off
.Lmla_nold8:
	global_load_dwordx4 v[132:135], v[166:167], off
	s_add_i32 s10, s69, 2
	s_and_b32 s10, s10, 6
	s_cmp_lg_u32 s10, 0
	s_cbranch_scc1 .Lmla_nomax9
	v_max3_f32 v96, v48, v49, v50
	v_max3_f32 v99, v32, v33, v34
	v_max3_f32 v98, v51, v52, v53
	v_max3_f32 v252, v35, v36, v37
	s_add_i32 s14, s69, 2
	s_and_b32 s14, s14, 56
	v_max3_f32 v96, v96, v54, v55
	v_max3_f32 v99, v99, v38, v39
	v_max3_f32 v98, v98, v56, v57
	v_max3_f32 v252, v252, v40, v41
	s_cmp_eq_u32 s14, 0
	v_max3_f32 v96, v96, v58, v59
	v_max3_f32 v99, v99, v42, v43
	v_max3_f32 v98, v98, v60, v61
	v_max3_f32 v252, v252, v44, v45
	s_cselect_b64 s[10:11], -1, 0
	v_max3_f32 v96, v96, v62, v63
	v_max3_f32 v99, v99, v46, v47
	s_cmp_lg_u32 s14, 0
	v_max3_f32 v96, v96, v98, v99
	s_nop 0
	v_max_f32_e32 v96, v96, v252
	s_nop 0
	v_mov_b32_e32 v98, v96
	s_nop 1
	v_permlane32_swap_b32_e32 v96, v98
	v_max_f32_e32 v98, v98, v98
	v_max_f32_e32 v96, v96, v96
	v_max_f32_e32 v96, v96, v98
	v_cmp_lt_f32_e32 vcc, s54, v96
	v_mov_b32_e32 v98, 0
	s_cbranch_scc1 .Lmla_mx10
	v_cmp_gt_f32_e64 s[14:15], s55, v96
	s_cmp_lg_u64 s[14:15], 0
	s_cselect_b64 s[14:15], -1, 0
	v_cndmask_b32_e64 v98, 0, 1, s[14:15]

; #define ATT_SUMPACK(j) do { const float e0_ = (j) < 8 ? P0[2 * ((j) & 7)] : P1[2 * ((j) & 7)], e1_ = (j) < 8 ? P0[2 * ((j) & 7) + 1] : P1[2 * ((j) & 7) + 1]; \
;         if ((j) & 1) { rc += e0_; rd += e1_; } else { ra += e0_; rb += e1_; } S.pw[j] = cvtpk(e0_, e1_); } while (0)
; template <int GRP, bool has_next> __device__ __forceinline__ void att_step(const AttCtx<GRP>& C, AttState<GRP>& S, int s, f32x16& P0, f32x16& P1, f32x16& PN0, f32x16& PN1, u32x4& kreg, u32x4& preg, u32x4& vreg) {
;     ...
;     float ra = 0.f, rb = 0.f, rc = 0.f, rd = 0.f;
;     ...
; #pragma unroll
;     for (int c = 1; c < NKS; ++c) {
;         if (has_next) {
;             if (c == NK0) att_kfrag<GRP, NK0, NK1>(C, (s + 1) & 1, kfb);
;             const bf16x8 a0 = c < NK0 ? kfa[2 * c] : kfb[2 * (c - NK0)], a1 = c < NK0 ? kfa[2 * c + 1] : kfb[2 * (c - NK0) + 1];
;             PN0 = __builtin_amdgcn_mfma_f32_32x32x16_bf16(a0, S.qr[c], PN0, 0, 0, 0); PN1 = __builtin_amdgcn_mfma_f32_32x32x16_bf16(a1, S.qr[c], PN1, 0, 0, 0);
;         }
; #pragma unroll
;         for (int j = (c - 1) * 16 / NE; j < c * 16 / NE; ++j) {
;             if (j < 8) { P0[2 * j] = __builtin_amdgcn_exp2f(P0[2 * j]); P0[2 * j + 1] = __builtin_amdgcn_exp2f(P0[2 * j + 1]); }
;             else { P1[2 * (j - 8)] = __builtin_amdgcn_exp2f(P1[2 * (j - 8)]); P1[2 * (j - 8) + 1] = __builtin_amdgcn_exp2f(P1[2 * (j - 8) + 1]); }
;         }
;         if (c > 1) {
; #pragma unroll
;             for (int j = (c - 2) * 16 / NE; j < (c - 1) * 16 / NE; ++j) ATT_SUMPACK(j);
;         }
;         __builtin_amdgcn_sched_barrier(0);
;     }
;     if (has_next && S.refnz && t != 63) { PN0 = __builtin_amdgcn_mfma_f32_32x32x16_bf16(ones, qx, PN0, 0, 0, 0); PN1 = __builtin_amdgcn_mfma_f32_32x32x16_bf16(ones, qx, PN1, 0, 0, 0); }
;     att_vfrag<GRP>(C, s & 1, vf);
; #pragma unroll
;     for (int j = (NE - 1) * 16 / NE; j < 16; ++j) ATT_SUMPACK(j);
;     ...
;     S.lrun += (ra + rb) + (rc + rd);
.Lmla_nomax9:
	v_exp_f32_e32 v48, v48
	v_exp_f32_e32 v49, v49
	v_exp_f32_e32 v50, v50
	v_exp_f32_e32 v51, v51
	v_cvt_pk_bf16_f32 v216, v48, v49
	v_exp_f32_e32 v52, v52
	v_exp_f32_e32 v53, v53
	v_cvt_pk_bf16_f32 v217, v50, v51
	v_exp_f32_e32 v54, v54
	v_exp_f32_e32 v55, v55
	v_add_f32_e32 v248, v48, v52
	v_add_f32_e32 v249, v49, v53
	v_cvt_pk_bf16_f32 v218, v52, v53
	v_exp_f32_e32 v56, v56
	v_exp_f32_e32 v57, v57
	v_add_f32_e32 v250, v50, v54
	v_add_f32_e32 v251, v51, v55
	v_cvt_pk_bf16_f32 v219, v54, v55
	v_exp_f32_e32 v58, v58
	v_exp_f32_e32 v59, v59
	v_add_f32_e32 v248, v248, v56
	v_add_f32_e32 v249, v249, v57
	v_cvt_pk_bf16_f32 v220, v56, v57
	v_exp_f32_e32 v60, v60
	v_exp_f32_e32 v61, v61
	v_add_f32_e32 v250, v250, v58
	v_add_f32_e32 v251, v251, v59
	v_cvt_pk_bf16_f32 v221, v58, v59
	v_exp_f32_e32 v62, v62
	v_exp_f32_e32 v63, v63
	v_add_f32_e32 v248, v248, v60
	v_add_f32_e32 v249, v249, v61
	v_cvt_pk_bf16_f32 v222, v60, v61
	v_exp_f32_e32 v32, v32
	v_exp_f32_e32 v33, v33
	v_add_f32_e32 v250, v250, v62
	v_add_f32_e32 v251, v251, v63
	v_cvt_pk_bf16_f32 v223, v62, v63
	v_exp_f32_e32 v34, v34
	v_exp_f32_e32 v35, v35
	v_add_f32_e32 v248, v248, v32
	v_add_f32_e32 v249, v249, v33
	v_cvt_pk_bf16_f32 v224, v32, v33
	v_exp_f32_e32 v36, v36
	v_exp_f32_e32 v37, v37
	v_add_f32_e32 v250, v250, v34
	v_add_f32_e32 v251, v251, v35
	v_cvt_pk_bf16_f32 v225, v34, v35
	v_exp_f32_e32 v38, v38
	v_exp_f32_e32 v39, v39
	v_add_f32_e32 v248, v248, v36
	v_add_f32_e32 v249, v249, v37
	v_cvt_pk_bf16_f32 v226, v36, v37
	v_exp_f32_e32 v40, v40
	v_exp_f32_e32 v41, v41
	v_add_f32_e32 v250, v250, v38
	v_add_f32_e32 v251, v251, v39
	v_cvt_pk_bf16_f32 v227, v38, v39
	v_exp_f32_e32 v42, v42
	v_exp_f32_e32 v43, v43
	v_add_f32_e32 v248, v248, v40
	v_add_f32_e32 v249, v249, v41
	v_cvt_pk_bf16_f32 v228, v40, v41
	v_exp_f32_e32 v44, v44
	v_exp_f32_e32 v45, v45
	v_add_f32_e32 v250, v250, v42
	v_add_f32_e32 v251, v251, v43
	v_cvt_pk_bf16_f32 v229, v42, v43
	v_exp_f32_e32 v46, v46
	v_exp_f32_e32 v47, v47
	v_add_f32_e32 v248, v248, v44
	v_add_f32_e32 v249, v249, v45
	v_cvt_pk_bf16_f32 v230, v44, v45
	v_add_f32_e32 v250, v250, v46
	v_add_f32_e32 v251, v251, v47
	v_cvt_pk_bf16_f32 v231, v46, v47
	v_add_f32_e32 v248, v248, v249
	v_add_f32_e32 v250, v250, v251
	v_add_f32_e32 v248, v248, v250
	v_add_f32_e32 v170, v170, v248
	s_waitcnt lgkmcnt(0)
	s_barrier
	s_add_i32 s10, s69, 2
	s_addk_i32 s70, 0x2000
	s_addk_i32 s67, 0x1000
	s_cmpk_gt_u32 s69, 0xfb
	v_lshl_add_u64 v[166:167], v[166:167], 0, s[64:65]
	s_cbranch_scc1 .Lmla_L_tail
	s_mov_b32 s69, s10
	s_branch .Lmla_L_loop

; #define ATT_BAR() do { __builtin_amdgcn_sched_barrier(0); asm volatile("s_waitcnt lgkmcnt(0)\n\ts_barrier" ::: "memory"); __builtin_amdgcn_sched_barrier(0); } while (0)
; #define ATT_SUMPACK(j) do { const float e0_ = (j) < 8 ? P0[2 * ((j) & 7)] : P1[2 * ((j) & 7)], e1_ = (j) < 8 ? P0[2 * ((j) & 7) + 1] : P1[2 * ((j) & 7) + 1]; \
;         if ((j) & 1) { rc += e0_; rd += e1_; } else { ra += e0_; rb += e1_; } S.pw[j] = cvtpk(e0_, e1_); } while (0)
; template <int GRP, bool has_next> __device__ __forceinline__ void att_step(const AttCtx<GRP>& C, AttState<GRP>& S, int s, f32x16& P0, f32x16& P1, f32x16& PN0, f32x16& PN1, u32x4& kreg, u32x4& preg, u32x4& vreg) {
;     ...
;     att_vfrag<GRP>(C, s & 1, vf);
; #pragma unroll
;     for (int j = (NE - 1) * 16 / NE; j < 16; ++j) ATT_SUMPACK(j);
;     ...
;     S.lrun += (ra + rb) + (rc + rd);
;     att_pv<GRP>(S, vf);
;     if (t == 63) {
;         att_finish_head<GRP>(C, S, h);
;         S.o0 = (f32x16){}; S.o1 = (f32x16){}; S.lrun = 0.f; S.mhat = 0.f; S.refnz = 0;
;     }
;     att_stld<GRP>(C, s, kreg, preg, vreg);
;     ATT_BAR();
; template <int GRP> ...
;     ...
;     for (int s = 0; s < NSTEP - 2; s += 2) { att_step<GRP, true>(C, S, s, pa0, pa1, pb0, pb1, kA, pA, vA); att_step<GRP, true>(C, S, s + 1, pb0, pb1, pa0, pa1, kA, pA, vA); }
;     att_step<GRP, true>(C, S, NSTEP - 2, pa0, pa1, pb0, pb1, kA, pA, vA); att_step<GRP, false>(C, S, NSTEP - 1, pb0, pb1, pa0, pa1, kA, pA, vA);
.Lmla_nrz11:
	s_waitcnt lgkmcnt(3)
	v_mfma_f32_32x32x16_bf16 v[0:15], v[232:235], v[216:219], v[0:15]
	ds_read_b128 v[232:235], v157 offset:26688
	s_waitcnt lgkmcnt(3)
	v_mfma_f32_32x32x16_bf16 v[16:31], v[236:239], v[216:219], v[16:31]
	ds_read_b128 v[236:239], v157 offset:31296
	s_waitcnt lgkmcnt(3)
	v_mfma_f32_32x32x16_bf16 v[0:15], v[240:243], v[220:223], v[0:15]
	ds_read_b128 v[240:243], v157 offset:26720
	s_waitcnt lgkmcnt(3)
	v_mfma_f32_32x32x16_bf16 v[16:31], v[244:247], v[220:223], v[16:31]
	ds_read_b128 v[244:247], v157 offset:31328
	s_waitcnt lgkmcnt(3)
	v_mfma_f32_32x32x16_bf16 v[0:15], v[232:235], v[224:227], v[0:15]
	s_waitcnt lgkmcnt(2)
	v_mfma_f32_32x32x16_bf16 v[16:31], v[236:239], v[224:227], v[16:31]
	s_waitcnt lgkmcnt(1)
	v_mfma_f32_32x32x16_bf16 v[0:15], v[240:243], v[228:231], v[0:15]
	s_waitcnt lgkmcnt(0)
	v_mfma_f32_32x32x16_bf16 v[16:31], v[244:247], v[228:231], v[16:31]
	s_waitcnt vmcnt(0)
	ds_write_b128 v169, v[132:135] offset:35840
	v_exp_f32_e32 v80, v80
	v_exp_f32_e32 v81, v81
	v_exp_f32_e32 v82, v82
	v_exp_f32_e32 v83, v83
	v_cvt_pk_bf16_f32 v216, v80, v81
	v_exp_f32_e32 v84, v84
	v_exp_f32_e32 v85, v85
	v_cvt_pk_bf16_f32 v217, v82, v83
	v_exp_f32_e32 v86, v86
	v_exp_f32_e32 v87, v87
	v_add_f32_e32 v248, v80, v84
	v_add_f32_e32 v249, v81, v85
	v_cvt_pk_bf16_f32 v218, v84, v85
	v_exp_f32_e32 v88, v88
	v_exp_f32_e32 v89, v89
	v_add_f32_e32 v250, v82, v86
	v_add_f32_e32 v251, v83, v87
	v_cvt_pk_bf16_f32 v219, v86, v87
	v_exp_f32_e32 v90, v90
	v_exp_f32_e32 v91, v91
	v_add_f32_e32 v248, v248, v88
	v_add_f32_e32 v249, v249, v89
	v_cvt_pk_bf16_f32 v220, v88, v89
	v_exp_f32_e32 v92, v92
	v_exp_f32_e32 v93, v93
	v_add_f32_e32 v250, v250, v90
	v_add_f32_e32 v251, v251, v91
	v_cvt_pk_bf16_f32 v221, v90, v91
	v_exp_f32_e32 v94, v94
	v_exp_f32_e32 v95, v95
	v_add_f32_e32 v248, v248, v92
	v_add_f32_e32 v249, v249, v93
	v_cvt_pk_bf16_f32 v222, v92, v93
	v_exp_f32_e32 v64, v64
	v_exp_f32_e32 v65, v65
	v_add_f32_e32 v250, v250, v94
	v_add_f32_e32 v251, v251, v95
	v_cvt_pk_bf16_f32 v223, v94, v95
	v_exp_f32_e32 v66, v66
	v_exp_f32_e32 v67, v67
	v_add_f32_e32 v248, v248, v64
	v_add_f32_e32 v249, v249, v65
	v_cvt_pk_bf16_f32 v224, v64, v65
	v_exp_f32_e32 v68, v68
	v_exp_f32_e32 v69, v69
	v_add_f32_e32 v250, v250, v66
	v_add_f32_e32 v251, v251, v67
	v_cvt_pk_bf16_f32 v225, v66, v67
	v_exp_f32_e32 v70, v70
	v_exp_f32_e32 v71, v71
	v_add_f32_e32 v248, v248, v68
	v_add_f32_e32 v249, v249, v69
	v_cvt_pk_bf16_f32 v226, v68, v69
	v_exp_f32_e32 v72, v72
	v_exp_f32_e32 v73, v73
	v_add_f32_e32 v250, v250, v70
	v_add_f32_e32 v251, v251, v71
	v_cvt_pk_bf16_f32 v227, v70, v71
	v_exp_f32_e32 v74, v74
	v_exp_f32_e32 v75, v75
	v_add_f32_e32 v248, v248, v72
	v_add_f32_e32 v249, v249, v73
	v_cvt_pk_bf16_f32 v228, v72, v73
	v_exp_f32_e32 v76, v76
	v_exp_f32_e32 v77, v77
	v_add_f32_e32 v250, v250, v74
	v_add_f32_e32 v251, v251, v75
	v_cvt_pk_bf16_f32 v229, v74, v75
	v_exp_f32_e32 v78, v78
	v_exp_f32_e32 v79, v79
	v_add_f32_e32 v248, v248, v76
	v_add_f32_e32 v249, v249, v77
	v_cvt_pk_bf16_f32 v230, v76, v77
	v_add_f32_e32 v250, v250, v78
	v_add_f32_e32 v251, v251, v79
	v_cvt_pk_bf16_f32 v231, v78, v79
	v_add_f32_e32 v248, v248, v249
	v_add_f32_e32 v250, v250, v251
	v_add_f32_e32 v248, v248, v250
	v_add_f32_e32 v170, v170, v248
	s_waitcnt lgkmcnt(0)
	s_barrier
	s_mov_b64 s[86:87], -1
	s_lshr_b32 s71, s69, 6
	s_add_i32 s71, s71, s60
	ds_read_b128 v[232:235], v157 offset:35840
	ds_read_b128 v[236:239], v157 offset:40448
	ds_read_b128 v[240:243], v157 offset:35872
	ds_read_b128 v[244:247], v157 offset:40480
	s_waitcnt lgkmcnt(3)
	v_mfma_f32_32x32x16_bf16 v[0:15], v[232:235], v[216:219], v[0:15]
	ds_read_b128 v[232:235], v157 offset:35904
	s_waitcnt lgkmcnt(3)
	v_mfma_f32_32x32x16_bf16 v[16:31], v[236:239], v[216:219], v[16:31]
	ds_read_b128 v[236:239], v157 offset:40512
	s_waitcnt lgkmcnt(3)
	v_mfma_f32_32x32x16_bf16 v[0:15], v[240:243], v[220:223], v[0:15]
	ds_read_b128 v[240:243], v157 offset:35936
	s_waitcnt lgkmcnt(3)
	v_mfma_f32_32x32x16_bf16 v[16:31], v[244:247], v[220:223], v[16:31]
	ds_read_b128 v[244:247], v157 offset:40544
	s_waitcnt lgkmcnt(3)
	v_mfma_f32_32x32x16_bf16 v[0:15], v[232:235], v[224:227], v[0:15]
	s_waitcnt lgkmcnt(2)
	v_mfma_f32_32x32x16_bf16 v[16:31], v[236:239], v[224:227], v[16:31]
	s_waitcnt lgkmcnt(1)
	v_mfma_f32_32x32x16_bf16 v[0:15], v[240:243], v[228:231], v[0:15]
	s_waitcnt lgkmcnt(0)
	v_mfma_f32_32x32x16_bf16 v[16:31], v[244:247], v[228:231], v[16:31]
	s_cmp_lg_u64 s[86:87], 0
	s_cbranch_scc0 .Lmla_nofin12
; __device__ __forceinline__ unsigned cvtpk(float lo, float hi) { f32x2_t v = {lo, hi}; bf16x2_t b = __builtin_convertvector(v, bf16x2_t); return __builtin_bit_cast(unsigned, b); }
; __device__ __forceinline__ float xhalf_max(float m) { auto rr = __builtin_amdgcn_permlane32_swap(__float_as_uint(m), __float_as_uint(m), false, false); return fmaxf(__uint_as_float(rr[0]), __uint_as_float(rr[1])); }
; __device__ __forceinline__ float xhalf_sum(float m) { auto rr = __builtin_amdgcn_permlane32_swap(__float_as_uint(m), __float_as_uint(m), false, false); return __uint_as_float(rr[0]) + __uint_as_float(rr[1]); }
; template <int GRP> __device__ __forceinline__ void att_finish_head(const AttCtx<GRP>& C, AttState<GRP>& S, int h) {
;     const float inv = 1.0f / xhalf_sum(S.lrun);
;     bf16_t* orow = C.O + C.qrow * 1024 + GRP * 512 + h * 64 + 4 * C.hi;
; #pragma unroll
;     for (int rr = 0; rr < 4; ++rr) {
;         const f32x4 v0 = (f32x4){S.o0[4 * rr], S.o0[4 * rr + 1], S.o0[4 * rr + 2], S.o0[4 * rr + 3]} * inv, v1 = (f32x4){S.o1[4 * rr], S.o1[4 * rr + 1], S.o1[4 * rr + 2], S.o1[4 * rr + 3]} * inv;
;         S.ssq += (v0[0] * v0[0] + v0[1] * v0[1]) + (v0[2] * v0[2] + v0[3] * v0[3]) + (v1[0] * v1[0] + v1[1] * v1[1]) + (v1[2] * v1[2] + v1[3] * v1[3]);
;         u32x2 s0, s1; s0.x = cvtpk(v0[0], v0[1]); s0.y = cvtpk(v0[2], v0[3]); s1.x = cvtpk(v1[0], v1[1]); s1.y = cvtpk(v1[2], v1[3]);
;         *(u32x2*)(orow + 8 * rr) = s0; *(u32x2*)(orow + 32 + 8 * rr) = s1;
;     }
; }
; template <int GRP, bool has_next> __device__ __forceinline__ void att_step(const AttCtx<GRP>& C, AttState<GRP>& S, int s, f32x16& P0, f32x16& P1, f32x16& PN0, f32x16& PN1, u32x4& kreg, u32x4& preg, u32x4& vreg) {
;     ...
;     if ((t & 7) == 0) {
;         float ma = max3f(P0[0], P0[1], P0[2]), mb = max3f(P0[3], P0[4], P0[5]), mc = max3f(P1[0], P1[1], P1[2]), md = max3f(P1[3], P1[4], P1[5]);
;         ma = max3f(ma, P0[6], P0[7]); mb = max3f(mb, P0[8], P0[9]); mc = max3f(mc, P1[6], P1[7]); md = max3f(md, P1[8], P1[9]);
;         ma = max3f(ma, P0[10], P0[11]); mb = max3f(mb, P0[12], P0[13]); mc = max3f(mc, P1[10], P1[11]); md = max3f(md, P1[12], P1[13]);
;         ma = max3f(ma, P0[14], P0[15]); mc = max3f(mc, P1[14], P1[15]); ma = max3f(ma, mb, mc); mb = md;
;         const float mx = xhalf_max(max2f(ma, mb));
;         const int up = __any(mx > THR), dn = (t == 0) ? __any(mx < -THR) : 0;
	s_nop 7
	s_nop 3
	v_mov_b32_e32 v64, v170
	s_nop 1
	v_permlane32_swap_b32_e32 v170, v64
	v_add_f32_e32 v64, v170, v64
	v_div_scale_f32 v65, s[10:11], v64, v64, 1.0
	v_rcp_f32_e32 v66, v65
	s_lshl_b32 s10, s71, 6
	s_ashr_i32 s11, s10, 31
	v_mov_b32_e32 v175, 0
	v_fma_f32 v67, -v65, v66, 1.0
	v_fmac_f32_e32 v66, v67, v66
	v_div_scale_f32 v67, vcc, 1.0, v64, 1.0
	v_mul_f32_e32 v68, v67, v66
	v_fma_f32 v69, -v65, v68, v67
	v_fmac_f32_e32 v68, v69, v66
	v_fma_f32 v65, -v65, v68, v67
	v_div_fmas_f32 v65, v65, v66, v68
	v_div_fixup_f32 v64, v65, v64, 1.0
	v_pk_mul_f32 v[0:1], v[0:1], v[64:65] op_sel_hi:[1,0]
	v_pk_mul_f32 v[2:3], v[2:3], v[64:65] op_sel_hi:[1,0]
	v_pk_mul_f32 v[70:71], v[0:1], v[0:1]
	v_pk_mul_f32 v[68:69], v[2:3], v[2:3]
	v_pk_mul_f32 v[16:17], v[16:17], v[64:65] op_sel_hi:[1,0]
	v_pk_mul_f32 v[18:19], v[18:19], v[64:65] op_sel_hi:[1,0]
	v_pk_mov_b32 v[72:73], v[70:71], v[68:69] op_sel:[1,0]
	v_mov_b32_e32 v71, v69
	v_pk_add_f32 v[68:69], v[72:73], v[70:71]
	v_pk_mul_f32 v[70:71], v[18:19], v[18:19]
	v_pk_mul_f32 v[72:73], v[16:17], v[16:17]
	v_mov_b32_e32 v74, v70
	v_mov_b32_e32 v75, v72
	v_mov_b32_e32 v72, v71
	v_pk_add_f32 v[70:71], v[74:75], v[72:73]
	v_add_f32_e32 v65, v68, v69
	v_add_f32_e32 v65, v71, v65
	v_add_f32_e32 v65, v70, v65
	v_lshl_add_u64 v[66:67], s[10:11], 1, v[162:163]
	v_add_f32_e32 v65, v168, v65
	v_cvt_pk_bf16_f32 v0, v0, v1
	v_cvt_pk_bf16_f32 v1, v2, v3
	v_cvt_pk_bf16_f32 v2, v16, v17
	v_cvt_pk_bf16_f32 v3, v18, v19
	global_store_dwordx2 v[66:67], v[0:1], off
	global_store_dwordx2 v[66:67], v[2:3], off offset:64
	v_pk_mul_f32 v[0:1], v[4:5], v[64:65] op_sel_hi:[1,0]
	v_pk_mul_f32 v[2:3], v[6:7], v[64:65] op_sel_hi:[1,0]
	v_pk_mul_f32 v[4:5], v[20:21], v[64:65] op_sel_hi:[1,0]
	v_pk_mul_f32 v[6:7], v[22:23], v[64:65] op_sel_hi:[1,0]
	v_pk_mul_f32 v[16:17], v[2:3], v[2:3]
	v_pk_mul_f32 v[18:19], v[0:1], v[0:1]
	v_cvt_pk_bf16_f32 v0, v0, v1
	v_cvt_pk_bf16_f32 v1, v2, v3
	v_cvt_pk_bf16_f32 v2, v4, v5
	v_cvt_pk_bf16_f32 v3, v6, v7
	global_store_dwordx2 v[66:67], v[0:1], off offset:16
	global_store_dwordx2 v[66:67], v[2:3], off offset:80
	v_pk_mul_f32 v[2:3], v[8:9], v[64:65] op_sel_hi:[1,0]
	v_pk_mov_b32 v[20:21], v[18:19], v[16:17] op_sel:[1,0]
	v_mul_f32_e32 v8, v2, v2
	v_mov_b32_e32 v19, v17
	v_pk_mul_f32 v[0:1], v[10:11], v[64:65] op_sel_hi:[1,0]
	v_pk_fma_f32 v[8:9], v[2:3], v[2:3], v[8:9] op_sel_hi:[1,1,0]
	v_pk_add_f32 v[16:17], v[20:21], v[18:19]
	v_pk_mul_f32 v[18:19], v[6:7], v[6:7]
	v_pk_mul_f32 v[20:21], v[4:5], v[4:5]
	v_pk_mul_f32 v[4:5], v[26:27], v[64:65] op_sel_hi:[1,0]
	v_pk_mul_f32 v[6:7], v[24:25], v[64:65] op_sel_hi:[1,0]
	v_mul_f32_e32 v8, v0, v0
	v_pk_fma_f32 v[10:11], v[0:1], v[0:1], v[8:9] op_sel_hi:[1,1,0]
	v_cvt_pk_bf16_f32 v2, v2, v3
	v_cvt_pk_bf16_f32 v3, v0, v1
	v_cvt_pk_bf16_f32 v0, v6, v7
	v_cvt_pk_bf16_f32 v1, v4, v5
	v_mov_b32_e32 v22, v18
	v_mov_b32_e32 v23, v20
	v_mov_b32_e32 v20, v19
	global_store_dwordx2 v[66:67], v[2:3], off offset:32
	global_store_dwordx2 v[66:67], v[0:1], off offset:96
	v_pk_mul_f32 v[0:1], v[12:13], v[64:65] op_sel_hi:[1,0]
	v_pk_add_f32 v[18:19], v[22:23], v[20:21]
	v_pk_mul_f32 v[2:3], v[14:15], v[64:65] op_sel_hi:[1,0]
	v_mov_b32_e32 v21, v6
	v_mov_b32_e32 v6, v1
	v_mul_f32_e32 v8, v2, v2
	v_mul_f32_e32 v10, v3, v3
	v_mov_b32_e32 v20, v0
	v_pk_mul_f32 v[6:7], v[6:7], v[6:7]
	v_pk_add_f32 v[16:17], v[16:17], v[16:17] op_sel:[0,1] op_sel_hi:[1,0]
	v_pk_mul_f32 v[12:13], v[28:29], v[64:65] op_sel_hi:[1,0]
	v_pk_fma_f32 v[6:7], v[20:21], v[20:21], v[6:7]
	v_pk_add_f32 v[8:9], v[8:9], v[10:11]
	v_pk_add_f32 v[16:17], v[18:19], v[16:17] op_sel:[1,0] op_sel_hi:[0,1]
	v_pk_add_f32 v[6:7], v[6:7], v[8:9]
	v_mov_b32_e32 v9, v4
	v_mov_b32_e32 v4, v13
	v_pk_add_f32 v[16:17], v[18:19], v[16:17]
	v_pk_mul_f32 v[14:15], v[30:31], v[64:65] op_sel_hi:[1,0]
	v_mov_b32_e32 v8, v12
	v_pk_mul_f32 v[4:5], v[4:5], v[4:5]
	v_mul_f32_e32 v18, v14, v14
	v_mul_f32_e32 v64, v15, v15
	v_pk_fma_f32 v[4:5], v[8:9], v[8:9], v[4:5]
	v_mov_b32_e32 v19, v16
	v_pk_add_f32 v[4:5], v[4:5], v[6:7]
	v_pk_add_f32 v[6:7], v[18:19], v[64:65]
	v_cvt_pk_bf16_f32 v0, v0, v1
	v_pk_add_f32 v[4:5], v[4:5], v[6:7]
	v_cvt_pk_bf16_f32 v1, v2, v3
	v_cvt_pk_bf16_f32 v2, v12, v13
	v_cvt_pk_bf16_f32 v3, v14, v15
	v_add_f32_e32 v168, v4, v5
	global_store_dwordx2 v[66:67], v[0:1], off offset:48
	global_store_dwordx2 v[66:67], v[2:3], off offset:112
	s_mov_b32 s72, 0
	v_mov_b32_e32 v170, 0
	v_mov_b32_e32 v0, 0
	v_mov_b32_e32 v1, v175
	v_mov_b32_e32 v2, v175
	v_mov_b32_e32 v3, v175
	v_mov_b32_e32 v4, v175
	v_mov_b32_e32 v5, v175
	v_mov_b32_e32 v6, v175
	v_mov_b32_e32 v7, v175
	v_mov_b32_e32 v8, v175
	v_mov_b32_e32 v9, v175
	v_mov_b32_e32 v10, v175
	v_mov_b32_e32 v11, v175
	v_mov_b32_e32 v12, v175
	v_mov_b32_e32 v13, v175
	v_mov_b32_e32 v14, v175
	v_mov_b32_e32 v15, v175
	v_mov_b32_e32 v16, 0
	v_mov_b32_e32 v17, v175
	v_mov_b32_e32 v18, v175
	v_mov_b32_e32 v19, v175
	v_mov_b32_e32 v20, v175
	v_mov_b32_e32 v21, v175
	v_mov_b32_e32 v22, v175
	v_mov_b32_e32 v23, v175
	v_mov_b32_e32 v24, v175
	v_mov_b32_e32 v25, v175
	v_mov_b32_e32 v26, v175
	v_mov_b32_e32 v27, v175
	v_mov_b32_e32 v28, v175
	v_mov_b32_e32 v29, v175
	v_mov_b32_e32 v30, v175
	v_mov_b32_e32 v31, v175
.Lmla_nofin12:
	s_waitcnt lgkmcnt(0)
	s_barrier
	v_mov_b32_e32 v0, v168
	s_lshl_b32 s14, s66, 8
	s_ashr_i32 s15, s14, 31
	s_branch .Lmla_join
.LBB0_776:
	s_waitcnt vmcnt(1)
	ds_write_b128 v171, v[104:107]
	s_mov_b32 s84, 0xfe000000
	s_mov_b32 s85, -1
	s_waitcnt vmcnt(0)
	ds_write_b128 v169, v[132:135] offset:35840
	v_lshl_add_u64 v[192:193], v[166:167], 0, s[84:85]
	global_load_dwordx4 v[104:107], v[192:193], off
	s_mov_b32 s84, 0xffffe000
	s_nop 0
	v_lshl_add_u64 v[192:193], v[166:167], 0, s[84:85]
	global_load_dwordx4 v[132:135], v[192:193], off
	s_and_b32 s10, s69, 6
	s_cmp_lg_u32 s10, 0
	s_cbranch_scc1 .Lmla_nomax13
	v_max3_f32 v96, v48, v49, v50
	v_max3_f32 v99, v32, v33, v34
	v_max3_f32 v98, v51, v52, v53
	v_max3_f32 v252, v35, v36, v37
	s_and_b32 s14, s69, 56
	v_max3_f32 v96, v96, v54, v55
	v_max3_f32 v99, v99, v38, v39
	v_max3_f32 v98, v98, v56, v57
	v_max3_f32 v252, v252, v40, v41
	s_cmp_eq_u32 s14, 0
	v_max3_f32 v96, v96, v58, v59
	v_max3_f32 v99, v99, v42, v43
	v_max3_f32 v98, v98, v60, v61
	v_max3_f32 v252, v252, v44, v45
	s_cselect_b64 s[10:11], -1, 0
	v_max3_f32 v96, v96, v62, v63
	v_max3_f32 v99, v99, v46, v47
	s_cmp_lg_u32 s14, 0
	v_max3_f32 v96, v96, v98, v99
	s_nop 0
	v_max_f32_e32 v96, v96, v252
	s_nop 0
	v_mov_b32_e32 v98, v96
	s_nop 1
	v_permlane32_swap_b32_e32 v96, v98
	v_max_f32_e32 v98, v98, v98
	v_max_f32_e32 v96, v96, v96
	v_max_f32_e32 v96, v96, v98
	v_cmp_lt_f32_e32 vcc, s54, v96
	v_mov_b32_e32 v98, 0
	s_cbranch_scc1 .Lmla_mx14
	v_cmp_gt_f32_e64 s[14:15], s55, v96
	s_cmp_lg_u64 s[14:15], 0
	s_cselect_b64 s[14:15], -1, 0
	v_cndmask_b32_e64 v98, 0, 1, s[14:15]

; #define ATT_SUMPACK(j) do { const float e0_ = (j) < 8 ? P0[2 * ((j) & 7)] : P1[2 * ((j) & 7)], e1_ = (j) < 8 ? P0[2 * ((j) & 7) + 1] : P1[2 * ((j) & 7) + 1]; \
;         if ((j) & 1) { rc += e0_; rd += e1_; } else { ra += e0_; rb += e1_; } S.pw[j] = cvtpk(e0_, e1_); } while (0)
; template <int GRP, bool has_next> __device__ __forceinline__ void att_step(const AttCtx<GRP>& C, AttState<GRP>& S, int s, f32x16& P0, f32x16& P1, f32x16& PN0, f32x16& PN1, u32x4& kreg, u32x4& preg, u32x4& vreg) {
;     ...
;     float ra = 0.f, rb = 0.f, rc = 0.f, rd = 0.f;
;     ...
; #pragma unroll
;     for (int c = 1; c < NKS; ++c) {
;         if (has_next) {
;             if (c == NK0) att_kfrag<GRP, NK0, NK1>(C, (s + 1) & 1, kfb);
;             const bf16x8 a0 = c < NK0 ? kfa[2 * c] : kfb[2 * (c - NK0)], a1 = c < NK0 ? kfa[2 * c + 1] : kfb[2 * (c - NK0) + 1];
;             PN0 = __builtin_amdgcn_mfma_f32_32x32x16_bf16(a0, S.qr[c], PN0, 0, 0, 0); PN1 = __builtin_amdgcn_mfma_f32_32x32x16_bf16(a1, S.qr[c], PN1, 0, 0, 0);
;         }
; #pragma unroll
;         for (int j = (c - 1) * 16 / NE; j < c * 16 / NE; ++j) {
;             if (j < 8) { P0[2 * j] = __builtin_amdgcn_exp2f(P0[2 * j]); P0[2 * j + 1] = __builtin_amdgcn_exp2f(P0[2 * j + 1]); }
;             else { P1[2 * (j - 8)] = __builtin_amdgcn_exp2f(P1[2 * (j - 8)]); P1[2 * (j - 8) + 1] = __builtin_amdgcn_exp2f(P1[2 * (j - 8) + 1]); }
;         }
;         if (c > 1) {
; #pragma unroll
;             for (int j = (c - 2) * 16 / NE; j < (c - 1) * 16 / NE; ++j) ATT_SUMPACK(j);
;         }
;         __builtin_amdgcn_sched_barrier(0);
;     }
;     if (has_next && S.refnz && t != 63) { PN0 = __builtin_amdgcn_mfma_f32_32x32x16_bf16(ones, qx, PN0, 0, 0, 0); PN1 = __builtin_amdgcn_mfma_f32_32x32x16_bf16(ones, qx, PN1, 0, 0, 0); }
.Lmla_nomax13:
	v_exp_f32_e32 v48, v48
	v_exp_f32_e32 v49, v49
	v_exp_f32_e32 v50, v50
	v_exp_f32_e32 v51, v51
	v_cvt_pk_bf16_f32 v216, v48, v49
	v_exp_f32_e32 v52, v52
	v_exp_f32_e32 v53, v53
	v_cvt_pk_bf16_f32 v217, v50, v51
	v_exp_f32_e32 v54, v54
	v_exp_f32_e32 v55, v55
	v_add_f32_e32 v248, v48, v52
	v_add_f32_e32 v249, v49, v53
	v_cvt_pk_bf16_f32 v218, v52, v53
	v_exp_f32_e32 v56, v56
	v_exp_f32_e32 v57, v57
	v_add_f32_e32 v250, v50, v54
	v_add_f32_e32 v251, v51, v55
	v_cvt_pk_bf16_f32 v219, v54, v55
	v_exp_f32_e32 v58, v58
	v_exp_f32_e32 v59, v59
	v_add_f32_e32 v248, v248, v56
	v_add_f32_e32 v249, v249, v57
	v_cvt_pk_bf16_f32 v220, v56, v57
	v_exp_f32_e32 v60, v60
	v_exp_f32_e32 v61, v61
	v_add_f32_e32 v250, v250, v58
	v_add_f32_e32 v251, v251, v59
	v_cvt_pk_bf16_f32 v221, v58, v59
	v_exp_f32_e32 v62, v62
	v_exp_f32_e32 v63, v63
	v_add_f32_e32 v248, v248, v60
	v_add_f32_e32 v249, v249, v61
	v_cvt_pk_bf16_f32 v222, v60, v61
	v_exp_f32_e32 v32, v32
	v_exp_f32_e32 v33, v33
	v_add_f32_e32 v250, v250, v62
	v_add_f32_e32 v251, v251, v63
	v_cvt_pk_bf16_f32 v223, v62, v63
	v_exp_f32_e32 v34, v34
	v_exp_f32_e32 v35, v35
	v_add_f32_e32 v248, v248, v32
	v_add_f32_e32 v249, v249, v33
	v_cvt_pk_bf16_f32 v224, v32, v33
	v_exp_f32_e32 v36, v36
	v_exp_f32_e32 v37, v37
	v_add_f32_e32 v250, v250, v34
	v_add_f32_e32 v251, v251, v35
	v_cvt_pk_bf16_f32 v225, v34, v35
	v_exp_f32_e32 v38, v38
	v_exp_f32_e32 v39, v39
	v_add_f32_e32 v248, v248, v36
	v_add_f32_e32 v249, v249, v37
	v_cvt_pk_bf16_f32 v226, v36, v37
	v_exp_f32_e32 v40, v40
	v_exp_f32_e32 v41, v41
	v_add_f32_e32 v250, v250, v38
	v_add_f32_e32 v251, v251, v39
	v_cvt_pk_bf16_f32 v227, v38, v39
	v_exp_f32_e32 v42, v42
	v_exp_f32_e32 v43, v43
	v_add_f32_e32 v248, v248, v40
	v_add_f32_e32 v249, v249, v41
	v_cvt_pk_bf16_f32 v228, v40, v41
	v_exp_f32_e32 v44, v44
	v_exp_f32_e32 v45, v45
	v_add_f32_e32 v250, v250, v42
	v_add_f32_e32 v251, v251, v43
	v_cvt_pk_bf16_f32 v229, v42, v43
	v_exp_f32_e32 v46, v46
	v_exp_f32_e32 v47, v47
	v_add_f32_e32 v248, v248, v44
	v_add_f32_e32 v249, v249, v45
	v_cvt_pk_bf16_f32 v230, v44, v45
	v_add_f32_e32 v250, v250, v46
	v_add_f32_e32 v251, v251, v47
	v_cvt_pk_bf16_f32 v231, v46, v47
	v_add_f32_e32 v248, v248, v249
	v_add_f32_e32 v250, v250, v251
	v_add_f32_e32 v248, v248, v250
	v_add_f32_e32 v170, v170, v248
	ds_read_b128 v[136:139], v174 offset:13312
	ds_read_b128 v[140:143], v174 offset:19968
	ds_read_b128 v[144:147], v174 offset:13344
	ds_read_b128 v[148:151], v174 offset:20000
	ds_read_b128 v[176:179], v174 offset:13376
	ds_read_b128 v[180:183], v174 offset:20032
	s_waitcnt lgkmcnt(5)
	v_mfma_f32_32x32x16_bf16 v[80:95], v[136:139], v[128:131], 0
	ds_read_b128 v[136:139], v174 offset:13408
	s_waitcnt lgkmcnt(5)
	v_mfma_f32_32x32x16_bf16 v[64:79], v[140:143], v[128:131], 0
	ds_read_b128 v[140:143], v174 offset:20064
	s_waitcnt lgkmcnt(5)
	v_mfma_f32_32x32x16_bf16 v[80:95], v[144:147], v[124:127], v[80:95]
	ds_read_b128 v[144:147], v174 offset:13440
	s_waitcnt lgkmcnt(5)
	v_mfma_f32_32x32x16_bf16 v[64:79], v[148:151], v[124:127], v[64:79]
	ds_read_b128 v[148:151], v174 offset:20096
	s_waitcnt lgkmcnt(5)
	v_mfma_f32_32x32x16_bf16 v[80:95], v[176:179], v[120:123], v[80:95]
	ds_read_b128 v[176:179], v174 offset:13472
	s_waitcnt lgkmcnt(5)
	v_mfma_f32_32x32x16_bf16 v[64:79], v[180:183], v[120:123], v[64:79]
	ds_read_b128 v[180:183], v174 offset:20128
	s_waitcnt lgkmcnt(5)
	v_mfma_f32_32x32x16_bf16 v[80:95], v[136:139], v[116:119], v[80:95]
	ds_read_b128 v[232:235], v157 offset:26624
	s_waitcnt lgkmcnt(5)
	v_mfma_f32_32x32x16_bf16 v[64:79], v[140:143], v[116:119], v[64:79]
	ds_read_b128 v[236:239], v157 offset:31232
	s_waitcnt lgkmcnt(5)
	v_mfma_f32_32x32x16_bf16 v[80:95], v[144:147], v[112:115], v[80:95]
	ds_read_b128 v[240:243], v157 offset:26656
	s_waitcnt lgkmcnt(5)
	v_mfma_f32_32x32x16_bf16 v[64:79], v[148:151], v[112:115], v[64:79]
	ds_read_b128 v[244:247], v157 offset:31264
	s_waitcnt lgkmcnt(5)
	v_mfma_f32_32x32x16_bf16 v[80:95], v[176:179], v[108:111], v[80:95]
	s_waitcnt lgkmcnt(4)
	v_mfma_f32_32x32x16_bf16 v[64:79], v[180:183], v[108:111], v[64:79]
	s_cmp_eq_u32 s72, 0
	s_cbranch_scc1 .Lmla_nrz15
	v_xor_b32_e32 v195, 0x80000000, v175
	s_mov_b32 s18, s16
	s_mov_b32 s19, s16
	s_mov_b32 s17, s16
	v_mov_b64_e32 v[186:187], s[18:19]
	v_mov_b64_e32 v[184:185], s[16:17]
	s_mov_b64 vcc, s[0:1]
	v_cndmask_b32_sdwa v96, v97, v195, vcc dst_sel:DWORD dst_unused:UNUSED_PAD src0_sel:DWORD src1_sel:WORD_1
	v_mov_b32_e32 v98, v97
	v_mov_b32_e32 v99, v97
	s_nop 1
	v_mfma_f32_32x32x16_bf16 v[80:95], v[184:187], v[96:99], v[80:95]
	v_mfma_f32_32x32x16_bf16 v[64:79], v[184:187], v[96:99], v[64:79]
; #define ATT_BAR() do { __builtin_amdgcn_sched_barrier(0); asm volatile("s_waitcnt lgkmcnt(0)\n\ts_barrier" ::: "memory"); __builtin_amdgcn_sched_barrier(0); } while (0)
; #define ATT_SUMPACK(j) do { const float e0_ = (j) < 8 ? P0[2 * ((j) & 7)] : P1[2 * ((j) & 7)], e1_ = (j) < 8 ? P0[2 * ((j) & 7) + 1] : P1[2 * ((j) & 7) + 1]; \
;         if ((j) & 1) { rc += e0_; rd += e1_; } else { ra += e0_; rb += e1_; } S.pw[j] = cvtpk(e0_, e1_); } while (0)
; template <int GRP, bool has_next> __device__ __forceinline__ void att_step(const AttCtx<GRP>& C, AttState<GRP>& S, int s, f32x16& P0, f32x16& P1, f32x16& PN0, f32x16& PN1, u32x4& kreg, u32x4& preg, u32x4& vreg) {
;     ...
;     att_vfrag<GRP>(C, s & 1, vf);
; #pragma unroll
;     for (int j = (NE - 1) * 16 / NE; j < 16; ++j) ATT_SUMPACK(j);
;     ...
;     S.lrun += (ra + rb) + (rc + rd);
;     att_pv<GRP>(S, vf);
;     if (t == 63) {
;         att_finish_head<GRP>(C, S, h);
;         S.o0 = (f32x16){}; S.o1 = (f32x16){}; S.lrun = 0.f; S.mhat = 0.f; S.refnz = 0;
;     }
;     att_stld<GRP>(C, s, kreg, preg, vreg);
;     ATT_BAR();
.Lmla_nrz15:
	s_waitcnt lgkmcnt(3)
	v_mfma_f32_32x32x16_bf16 v[0:15], v[232:235], v[216:219], v[0:15]
	ds_read_b128 v[232:235], v157 offset:26688
	s_waitcnt lgkmcnt(3)
	v_mfma_f32_32x32x16_bf16 v[16:31], v[236:239], v[216:219], v[16:31]
	ds_read_b128 v[236:239], v157 offset:31296
	s_waitcnt lgkmcnt(3)
	v_mfma_f32_32x32x16_bf16 v[0:15], v[240:243], v[220:223], v[0:15]
	ds_read_b128 v[240:243], v157 offset:26720
	s_waitcnt lgkmcnt(3)
	v_mfma_f32_32x32x16_bf16 v[16:31], v[244:247], v[220:223], v[16:31]
	ds_read_b128 v[244:247], v157 offset:31328
	s_waitcnt lgkmcnt(3)
	v_mfma_f32_32x32x16_bf16 v[0:15], v[232:235], v[224:227], v[0:15]
	s_waitcnt lgkmcnt(2)
	v_mfma_f32_32x32x16_bf16 v[16:31], v[236:239], v[224:227], v[16:31]
	s_waitcnt lgkmcnt(1)
	v_mfma_f32_32x32x16_bf16 v[0:15], v[240:243], v[228:231], v[0:15]
	s_waitcnt lgkmcnt(0)
	v_mfma_f32_32x32x16_bf16 v[16:31], v[244:247], v[228:231], v[16:31]
	s_waitcnt lgkmcnt(0)
	s_barrier
	s_add_i32 s62, s69, 1
	s_lshr_b32 s71, s69, 6
	s_add_i32 s71, s71, s60
	s_and_b32 s10, s62, 63
	s_cmp_eq_u32 s10, 63
	s_cselect_b64 s[86:87], -1, 0
	s_waitcnt vmcnt(1)
	ds_write_b128 v171, v[104:107] offset:13312
	s_waitcnt vmcnt(0)
	ds_write_b128 v173, v[132:135] offset:26624
	s_cmpk_gt_u32 s62, 0xfc
	s_cbranch_scc1 .Lmla_nold17
	s_mov_b32 s88, s70
	s_ashr_i32 s89, s70, 31
	v_lshl_add_u64 v[192:193], s[88:89], 1, v[158:159]
	global_load_dwordx4 v[104:107], v[192:193], off
.Lmla_nold17:
	global_load_dwordx4 v[132:135], v[166:167], off
	v_exp_f32_e32 v80, v80
	v_exp_f32_e32 v81, v81
	v_exp_f32_e32 v82, v82
	v_exp_f32_e32 v83, v83
	v_cvt_pk_bf16_f32 v216, v80, v81
	v_exp_f32_e32 v84, v84
	v_exp_f32_e32 v85, v85
	v_cvt_pk_bf16_f32 v217, v82, v83
	v_exp_f32_e32 v86, v86
	v_exp_f32_e32 v87, v87
	v_add_f32_e32 v248, v80, v84
	v_add_f32_e32 v249, v81, v85
	v_cvt_pk_bf16_f32 v218, v84, v85
	v_exp_f32_e32 v88, v88
	v_exp_f32_e32 v89, v89
	v_add_f32_e32 v250, v82, v86
	v_add_f32_e32 v251, v83, v87
	v_cvt_pk_bf16_f32 v219, v86, v87
	v_exp_f32_e32 v90, v90
	v_exp_f32_e32 v91, v91
	v_add_f32_e32 v248, v248, v88
	v_add_f32_e32 v249, v249, v89
	v_cvt_pk_bf16_f32 v220, v88, v89
	v_exp_f32_e32 v92, v92
	v_exp_f32_e32 v93, v93
	v_add_f32_e32 v250, v250, v90
	v_add_f32_e32 v251, v251, v91
	v_cvt_pk_bf16_f32 v221, v90, v91
	v_exp_f32_e32 v94, v94
	v_exp_f32_e32 v95, v95
	v_add_f32_e32 v248, v248, v92
	v_add_f32_e32 v249, v249, v93
	v_cvt_pk_bf16_f32 v222, v92, v93
	v_exp_f32_e32 v64, v64
	v_exp_f32_e32 v65, v65
	v_add_f32_e32 v250, v250, v94
	v_add_f32_e32 v251, v251, v95
	v_cvt_pk_bf16_f32 v223, v94, v95
	v_exp_f32_e32 v66, v66
	v_exp_f32_e32 v67, v67
	v_add_f32_e32 v248, v248, v64
	v_add_f32_e32 v249, v249, v65
	v_cvt_pk_bf16_f32 v224, v64, v65
	v_exp_f32_e32 v68, v68
	v_exp_f32_e32 v69, v69
	v_add_f32_e32 v250, v250, v66
	v_add_f32_e32 v251, v251, v67
	v_cvt_pk_bf16_f32 v225, v66, v67
	v_exp_f32_e32 v70, v70
	v_exp_f32_e32 v71, v71
	v_add_f32_e32 v248, v248, v68
	v_add_f32_e32 v249, v249, v69
	v_cvt_pk_bf16_f32 v226, v68, v69
	v_exp_f32_e32 v72, v72
	v_exp_f32_e32 v73, v73
	v_add_f32_e32 v250, v250, v70
	v_add_f32_e32 v251, v251, v71
	v_cvt_pk_bf16_f32 v227, v70, v71
	v_exp_f32_e32 v74, v74
	v_exp_f32_e32 v75, v75
	v_add_f32_e32 v248, v248, v72
	v_add_f32_e32 v249, v249, v73
	v_cvt_pk_bf16_f32 v228, v72, v73
	v_exp_f32_e32 v76, v76
	v_exp_f32_e32 v77, v77
	v_add_f32_e32 v250, v250, v74
	v_add_f32_e32 v251, v251, v75
	v_cvt_pk_bf16_f32 v229, v74, v75
	v_exp_f32_e32 v78, v78
	v_exp_f32_e32 v79, v79
	v_add_f32_e32 v248, v248, v76
	v_add_f32_e32 v249, v249, v77
	v_cvt_pk_bf16_f32 v230, v76, v77
	v_add_f32_e32 v250, v250, v78
	v_add_f32_e32 v251, v251, v79
	v_cvt_pk_bf16_f32 v231, v78, v79
	v_add_f32_e32 v248, v248, v249
	v_add_f32_e32 v250, v250, v251
	v_add_f32_e32 v248, v248, v250
	v_add_f32_e32 v170, v170, v248
	s_cmp_lg_u64 s[86:87], 0
	s_cbranch_scc0 .Lmla_noq18
	s_mul_i32 s18, s71, 0x60
	s_ashr_i32 s19, s18, 31
	v_lshl_add_u64 v[192:193], s[18:19], 1, v[164:165]
	global_load_dwordx4 v[128:131], v[192:193], off offset:192
	global_load_dwordx4 v[124:127], v[192:193], off offset:224
	global_load_dwordx4 v[120:123], v[192:193], off offset:256
	global_load_dwordx4 v[116:119], v[192:193], off offset:288
	global_load_dwordx4 v[112:115], v[192:193], off offset:320
	global_load_dwordx4 v[108:111], v[192:193], off offset:352
	s_waitcnt vmcnt(0)

; template <int GRP> ...
;     ...
;     for (int s = 0; s < NSTEP - 2; s += 2) { att_step<GRP, true>(C, S, s, pa0, pa1, pb0, pb1, kA, pA, vA); att_step<GRP, true>(C, S, s + 1, pb0, pb1, pa0, pa1, kA, pA, vA); }
.Lmla_nofin20:
	s_waitcnt lgkmcnt(0)
	s_barrier
	s_add_i32 s10, s69, 2
	s_addk_i32 s70, 0x2000
	s_addk_i32 s67, 0x1000
	s_cmpk_gt_u32 s69, 0xfb
	v_lshl_add_u64 v[166:167], v[166:167], 0, s[64:65]
	s_cbranch_scc1 .LBB0_801
	s_mov_b32 s69, s10
	s_branch .LBB0_776

; __device__ __forceinline__ float xhalf_sum(float m) { auto rr = __builtin_amdgcn_permlane32_swap(__float_as_uint(m), __float_as_uint(m), false, false); return __uint_as_float(rr[0]) + __uint_as_float(rr[1]); }
; template <int GRP> ...
;     ...
;     __builtin_amdgcn_s_setprio(0);
;     const float ssq = xhalf_sum(S.ssq);
;     if (hi == 0) RS[C.qrow * 4 + GRP * 2 + hh] = ssq;
.Lmla_join:
	s_setprio 0
	v_mov_b32_e32 v1, v0
	s_nop 1
	v_permlane32_swap_b32_e32 v0, v1
	s_and_saveexec_b64 s[6:7], s[0:1]
	s_cbranch_execz .LBB0_805
	v_add_f32_e32 v2, v0, v1
	v_lshl_add_u64 v[0:1], v[152:153], 4, s[46:47]
	s_ashr_i32 s67, s66, 31
	v_lshl_add_u64 v[0:1], s[66:67], 2, v[0:1]
	global_store_dword v[0:1], v2, off
